# baseline (speedup 1.0000x reference)
; __device__ __forceinline__ void phase_fixup(PP p, const int g_wid, const float alpha_in) {
;     ...
;   if (bid < 16) {
;     float alpha = alpha_in; asm volatile("" : "+v"(alpha));
;     const int pn = bid & 3, bj = (bid >> 2) & 1, n = bid >> 3;
;     const int wid = tid >> 6, lane = tid & 63, wr = wid >> 2, wc = wid & 3, fr = lane & 15, fq = lane >> 4;
;     const f32x4* pb = reinterpret_cast<const f32x4*>(p->X + X_PB) + tid;
;     float* ssq = p->ssq;
;     const unsigned foff = wr * 64 + fq * 4;
;     const int row = 192 * 256 + wc * 32 + fr + bj * 128 + n * 16;
;     const bool ok = row < NTOK;
;     float sq = 0.f;
;     if (ok) {
;       u16* hbr = p->hb + (long)row * 1024 + pn * 256 + foff;
; #pragma unroll
;       for (int ai = 0; ai < 2; ++ai)
; #pragma unroll
;         for (int m = 0; m < 4; ++m) {
;           const int q = ((ai * 2 + bj) * 4 + m) * 2 + n;
;           f32x4 s = pb[((long)pn * 32 + q) * 512];
; #pragma unroll
;           for (int ks = 1; ks < 11; ++ks) s += pb[((long)(ks * 4 + pn) * 32 + q) * 512];
.LBB0_323:
	v_readlane_b32 s2, v254, 2
	s_lshl_b32 s3, s2, 6
	s_mov_b32 s2, -1
	v_writelane_b32 v254, s3, 63
	s_waitcnt lgkmcnt(0)
	v_mbcnt_lo_u32_b32 v0, s2, 0
	v_mbcnt_hi_u32_b32 v0, s2, v0
	v_or_b32_e32 v6, s3, v0
	v_readlane_b32 s2, v254, 3
	s_cmp_gt_i32 s2, 15
	s_cbranch_scc1 .LBB0_329
	s_mov_b32 s3, s2
	s_and_b32 s4, s3, 3
	s_bfe_u32 s5, s3, 0x10002
	s_lshr_b32 s6, s3, 3
	v_readlane_b32 s7, v254, 2
	v_readlane_b32 s16, v254, 0
	v_readlane_b32 s17, v254, 1
	s_load_dwordx2 s[8:9], s[16:17], 0xd0
	s_load_dwordx2 s[12:13], s[16:17], 0xc8
	s_load_dwordx2 s[14:15], s[16:17], 0xe0
	v_mbcnt_lo_u32_b32 v160, -1, 0
	v_mbcnt_hi_u32_b32 v160, -1, v160
	s_lshl_b32 s2, s7, 6
	v_or_b32_e32 v161, s2, v160
	v_and_b32_e32 v162, 15, v160
	v_lshrrev_b32_e32 v163, 4, v160
	s_and_b32 s2, s7, 3
	s_lshl_b32 s2, s2, 5
	s_lshl_b32 s11, s5, 7
	s_add_i32 s2, s2, s11
	s_lshl_b32 s11, s6, 4
	s_add_i32 s2, s2, s11
	v_add_u32_e32 v164, s2, v162
	v_add_u32_e32 v164, 0xc000, v164
	s_lshl_b32 s2, s4, 5
	s_lshl_b32 s11, s5, 3
	s_add_i32 s2, s2, s11
	s_add_i32 s2, s2, s6
	s_lshl_b32 s2, s2, 13
	s_waitcnt lgkmcnt(0)
	s_add_u32 s8, s8, 0x10960000
	s_addc_u32 s9, s9, 0
	s_add_u32 s8, s8, s2
	s_addc_u32 s9, s9, 0
	v_lshlrev_b32_e32 v174, 4, v161
	v_mov_b32_e32 v175, 0
	v_lshl_add_u64 v[166:167], s[8:9], 0, v[174:175]
	s_lshr_b32 s2, s7, 2
	s_lshl_b32 s2, s2, 7
	s_lshl_b32 s11, s4, 9
	s_add_i32 s2, s2, s11
	v_lshl_add_u32 v176, v163, 3, s2
	v_lshlrev_b32_e32 v177, 11, v164
	v_add_u32_e32 v176, v176, v177
	v_mov_b32_e32 v177, 0
	v_lshl_add_u64 v[168:169], s[12:13], 0, v[176:177]
	v_mov_b32_e32 v170, 0
	v_cmp_gt_u32_e32 vcc, 0xc0a0, v164
	s_and_saveexec_b64 s[16:17], vcc
	s_cbranch_execz .Lfx0_skip
	s_mov_b64 s[18:19], 0x100000
	v_mov_b64_e32 v[172:173], v[166:167]
	global_load_dwordx4 v[180:183], v[172:173], off
	v_lshl_add_u64 v[172:173], v[172:173], 0, s[18:19]
	global_load_dwordx4 v[184:187], v[172:173], off
	v_lshl_add_u64 v[172:173], v[172:173], 0, s[18:19]
	global_load_dwordx4 v[188:191], v[172:173], off
	v_lshl_add_u64 v[172:173], v[172:173], 0, s[18:19]
	global_load_dwordx4 v[192:195], v[172:173], off
	v_lshl_add_u64 v[172:173], v[172:173], 0, s[18:19]
	global_load_dwordx4 v[196:199], v[172:173], off
	v_lshl_add_u64 v[172:173], v[172:173], 0, s[18:19]
	global_load_dwordx4 v[200:203], v[172:173], off
	v_lshl_add_u64 v[172:173], v[172:173], 0, s[18:19]
	global_load_dwordx4 v[204:207], v[172:173], off
	v_lshl_add_u64 v[172:173], v[172:173], 0, s[18:19]
	global_load_dwordx4 v[208:211], v[172:173], off
	v_lshl_add_u64 v[172:173], v[172:173], 0, s[18:19]
	global_load_dwordx4 v[212:215], v[172:173], off
	v_lshl_add_u64 v[172:173], v[172:173], 0, s[18:19]
	global_load_dwordx4 v[216:219], v[172:173], off
	v_lshl_add_u64 v[172:173], v[172:173], 0, s[18:19]
	global_load_dwordx4 v[220:223], v[172:173], off
	global_load_dwordx2 v[224:225], v[168:169], off
	s_waitcnt vmcnt(10)
	v_add_f32_e32 v226, v180, v184
	v_add_f32_e32 v227, v181, v185
	v_add_f32_e32 v228, v182, v186
	v_add_f32_e32 v229, v183, v187
	s_waitcnt vmcnt(9)
	v_add_f32_e32 v226, v226, v188
	v_add_f32_e32 v227, v227, v189
	v_add_f32_e32 v228, v228, v190
	v_add_f32_e32 v229, v229, v191
	s_waitcnt vmcnt(8)
	v_add_f32_e32 v226, v226, v192
	v_add_f32_e32 v227, v227, v193
	v_add_f32_e32 v228, v228, v194
	v_add_f32_e32 v229, v229, v195
	s_waitcnt vmcnt(7)
	v_add_f32_e32 v226, v226, v196
	v_add_f32_e32 v227, v227, v197
	v_add_f32_e32 v228, v228, v198
	v_add_f32_e32 v229, v229, v199
	s_waitcnt vmcnt(6)
	v_add_f32_e32 v226, v226, v200
	v_add_f32_e32 v227, v227, v201
	v_add_f32_e32 v228, v228, v202
	v_add_f32_e32 v229, v229, v203
	s_waitcnt vmcnt(5)
	v_add_f32_e32 v226, v226, v204
	v_add_f32_e32 v227, v227, v205
	v_add_f32_e32 v228, v228, v206
	v_add_f32_e32 v229, v229, v207
	s_waitcnt vmcnt(4)
	v_add_f32_e32 v226, v226, v208
	v_add_f32_e32 v227, v227, v209
	v_add_f32_e32 v228, v228, v210
	v_add_f32_e32 v229, v229, v211
	s_waitcnt vmcnt(3)
	v_add_f32_e32 v226, v226, v212
	v_add_f32_e32 v227, v227, v213
	v_add_f32_e32 v228, v228, v214
	v_add_f32_e32 v229, v229, v215
	s_waitcnt vmcnt(2)
	v_add_f32_e32 v226, v226, v216
	v_add_f32_e32 v227, v227, v217
	v_add_f32_e32 v228, v228, v218
	v_add_f32_e32 v229, v229, v219
	s_waitcnt vmcnt(1)
	v_add_f32_e32 v226, v226, v220
	v_add_f32_e32 v227, v227, v221
	v_add_f32_e32 v228, v228, v222
	v_add_f32_e32 v229, v229, v223
	s_mov_b64 s[8:9], 0x4000
	v_lshl_add_u64 v[172:173], v[166:167], 0, s[8:9]
	global_load_dwordx4 v[180:183], v[172:173], off
	v_lshl_add_u64 v[172:173], v[172:173], 0, s[18:19]
	global_load_dwordx4 v[184:187], v[172:173], off
	v_lshl_add_u64 v[172:173], v[172:173], 0, s[18:19]
	global_load_dwordx4 v[188:191], v[172:173], off
	v_lshl_add_u64 v[172:173], v[172:173], 0, s[18:19]
	global_load_dwordx4 v[192:195], v[172:173], off
	v_lshl_add_u64 v[172:173], v[172:173], 0, s[18:19]
	global_load_dwordx4 v[196:199], v[172:173], off
	v_lshl_add_u64 v[172:173], v[172:173], 0, s[18:19]
	global_load_dwordx4 v[200:203], v[172:173], off
	v_lshl_add_u64 v[172:173], v[172:173], 0, s[18:19]
	global_load_dwordx4 v[204:207], v[172:173], off
	v_lshl_add_u64 v[172:173], v[172:173], 0, s[18:19]
	global_load_dwordx4 v[208:211], v[172:173], off
	v_lshl_add_u64 v[172:173], v[172:173], 0, s[18:19]
	global_load_dwordx4 v[212:215], v[172:173], off
	v_lshl_add_u64 v[172:173], v[172:173], 0, s[18:19]
	global_load_dwordx4 v[216:219], v[172:173], off
	v_lshl_add_u64 v[172:173], v[172:173], 0, s[18:19]
	global_load_dwordx4 v[220:223], v[172:173], off
	global_load_dwordx2 v[238:239], v[168:169], off offset:32
	s_waitcnt vmcnt(12)
; __device__ __forceinline__ float bf2f(u16 h) { return __uint_as_float(((unsigned)h) << 16); }
; __device__ __forceinline__ void phase_fixup(PP p, const int g_wid, const float alpha_in) {
;     ...
;       for (int ai = 0; ai < 2; ++ai)
; #pragma unroll
;         for (int m = 0; m < 4; ++m) {
;           const int q = ((ai * 2 + bj) * 4 + m) * 2 + n;
;           f32x4 s = pb[((long)pn * 32 + q) * 512];
; #pragma unroll
;           for (int ks = 1; ks < 11; ++ks) s += pb[((long)(ks * 4 + pn) * 32 + q) * 512];
;           const u16x4 ho = *reinterpret_cast<const u16x4*>(hbr + ai * 128 + m * 16);
;           float4 hv;
;           hv.x = bf2f(ho[0]) + alpha * s[0]; hv.y = bf2f(ho[1]) + alpha * s[1];
;           hv.z = bf2f(ho[2]) + alpha * s[2]; hv.w = bf2f(ho[3]) + alpha * s[3];
;           *reinterpret_cast<u16x4*>(hbr + ai * 128 + m * 16) = pack4(hv.x, hv.y, hv.z, hv.w);
;           sq += (hv.x * hv.x + hv.y * hv.y) + (hv.z * hv.z + hv.w * hv.w);
;         }
	v_lshlrev_b32_e32 v230, 16, v224
	v_and_b32_e32 v231, 0xffff0000, v224
	v_lshlrev_b32_e32 v232, 16, v225
	v_and_b32_e32 v233, 0xffff0000, v225
	v_fma_f32 v230, 0.5, v226, v230
	v_fma_f32 v231, 0.5, v227, v231
	v_fma_f32 v232, 0.5, v228, v232
	v_fma_f32 v233, 0.5, v229, v233
	v_cvt_pk_bf16_f32 v234, v230, v231
	v_cvt_pk_bf16_f32 v235, v232, v233
	global_store_dwordx2 v[168:169], v[234:235], off
	v_mul_f32_e32 v236, v231, v231
	v_fma_f32 v236, v230, v230, v236
	v_mul_f32_e32 v237, v233, v233
	v_fma_f32 v237, v232, v232, v237
	v_add_f32_e32 v236, v236, v237
	v_add_f32_e32 v170, v170, v236
	s_waitcnt vmcnt(11)
	v_add_f32_e32 v226, v180, v184
	v_add_f32_e32 v227, v181, v185
	v_add_f32_e32 v228, v182, v186
	v_add_f32_e32 v229, v183, v187
	s_waitcnt vmcnt(10)
	v_add_f32_e32 v226, v226, v188
	v_add_f32_e32 v227, v227, v189
	v_add_f32_e32 v228, v228, v190
	v_add_f32_e32 v229, v229, v191
	s_waitcnt vmcnt(9)
	v_add_f32_e32 v226, v226, v192
	v_add_f32_e32 v227, v227, v193
	v_add_f32_e32 v228, v228, v194
	v_add_f32_e32 v229, v229, v195
	s_waitcnt vmcnt(8)
	v_add_f32_e32 v226, v226, v196
	v_add_f32_e32 v227, v227, v197
	v_add_f32_e32 v228, v228, v198
	v_add_f32_e32 v229, v229, v199
	s_waitcnt vmcnt(7)
	v_add_f32_e32 v226, v226, v200
	v_add_f32_e32 v227, v227, v201
	v_add_f32_e32 v228, v228, v202
	v_add_f32_e32 v229, v229, v203
	s_waitcnt vmcnt(6)
	v_add_f32_e32 v226, v226, v204
	v_add_f32_e32 v227, v227, v205
	v_add_f32_e32 v228, v228, v206
	v_add_f32_e32 v229, v229, v207
	s_waitcnt vmcnt(5)
	v_add_f32_e32 v226, v226, v208
	v_add_f32_e32 v227, v227, v209
	v_add_f32_e32 v228, v228, v210
	v_add_f32_e32 v229, v229, v211
	s_waitcnt vmcnt(4)
	v_add_f32_e32 v226, v226, v212
	v_add_f32_e32 v227, v227, v213
	v_add_f32_e32 v228, v228, v214
	v_add_f32_e32 v229, v229, v215
	s_waitcnt vmcnt(3)
	v_add_f32_e32 v226, v226, v216
	v_add_f32_e32 v227, v227, v217
	v_add_f32_e32 v228, v228, v218
	v_add_f32_e32 v229, v229, v219
	s_waitcnt vmcnt(2)
	v_add_f32_e32 v226, v226, v220
	v_add_f32_e32 v227, v227, v221
	v_add_f32_e32 v228, v228, v222
	v_add_f32_e32 v229, v229, v223
	s_mov_b64 s[8:9], 0x8000
	v_lshl_add_u64 v[172:173], v[166:167], 0, s[8:9]
	global_load_dwordx4 v[180:183], v[172:173], off
	v_lshl_add_u64 v[172:173], v[172:173], 0, s[18:19]
	global_load_dwordx4 v[184:187], v[172:173], off
	v_lshl_add_u64 v[172:173], v[172:173], 0, s[18:19]
	global_load_dwordx4 v[188:191], v[172:173], off
	v_lshl_add_u64 v[172:173], v[172:173], 0, s[18:19]
	global_load_dwordx4 v[192:195], v[172:173], off
	v_lshl_add_u64 v[172:173], v[172:173], 0, s[18:19]
	global_load_dwordx4 v[196:199], v[172:173], off
	v_lshl_add_u64 v[172:173], v[172:173], 0, s[18:19]
	global_load_dwordx4 v[200:203], v[172:173], off
	v_lshl_add_u64 v[172:173], v[172:173], 0, s[18:19]
	global_load_dwordx4 v[204:207], v[172:173], off
	v_lshl_add_u64 v[172:173], v[172:173], 0, s[18:19]
	global_load_dwordx4 v[208:211], v[172:173], off
	v_lshl_add_u64 v[172:173], v[172:173], 0, s[18:19]
	global_load_dwordx4 v[212:215], v[172:173], off
	v_lshl_add_u64 v[172:173], v[172:173], 0, s[18:19]
	global_load_dwordx4 v[216:219], v[172:173], off
	v_lshl_add_u64 v[172:173], v[172:173], 0, s[18:19]
	global_load_dwordx4 v[220:223], v[172:173], off
	global_load_dwordx2 v[224:225], v[168:169], off offset:64
	s_waitcnt vmcnt(13)
	v_lshlrev_b32_e32 v230, 16, v238
	v_and_b32_e32 v231, 0xffff0000, v238
	v_lshlrev_b32_e32 v232, 16, v239
	v_and_b32_e32 v233, 0xffff0000, v239
	v_fma_f32 v230, 0.5, v226, v230
	v_fma_f32 v231, 0.5, v227, v231
	v_fma_f32 v232, 0.5, v228, v232
	v_fma_f32 v233, 0.5, v229, v233
	v_cvt_pk_bf16_f32 v234, v230, v231
	v_cvt_pk_bf16_f32 v235, v232, v233
	global_store_dwordx2 v[168:169], v[234:235], off offset:32
	v_mul_f32_e32 v236, v231, v231
	v_fma_f32 v236, v230, v230, v236
	v_mul_f32_e32 v237, v233, v233
	v_fma_f32 v237, v232, v232, v237
	v_add_f32_e32 v236, v236, v237
	v_add_f32_e32 v170, v170, v236
	s_waitcnt vmcnt(11)
	v_add_f32_e32 v226, v180, v184
	v_add_f32_e32 v227, v181, v185
	v_add_f32_e32 v228, v182, v186
	v_add_f32_e32 v229, v183, v187
	s_waitcnt vmcnt(10)
	v_add_f32_e32 v226, v226, v188
	v_add_f32_e32 v227, v227, v189
	v_add_f32_e32 v228, v228, v190
	v_add_f32_e32 v229, v229, v191
	s_waitcnt vmcnt(9)
	v_add_f32_e32 v226, v226, v192
	v_add_f32_e32 v227, v227, v193
	v_add_f32_e32 v228, v228, v194
	v_add_f32_e32 v229, v229, v195
	s_waitcnt vmcnt(8)
	v_add_f32_e32 v226, v226, v196
	v_add_f32_e32 v227, v227, v197
	v_add_f32_e32 v228, v228, v198
	v_add_f32_e32 v229, v229, v199
	s_waitcnt vmcnt(7)
	v_add_f32_e32 v226, v226, v200
	v_add_f32_e32 v227, v227, v201
	v_add_f32_e32 v228, v228, v202
	v_add_f32_e32 v229, v229, v203
	s_waitcnt vmcnt(6)
	v_add_f32_e32 v226, v226, v204
	v_add_f32_e32 v227, v227, v205
	v_add_f32_e32 v228, v228, v206
	v_add_f32_e32 v229, v229, v207
	s_waitcnt vmcnt(5)
	v_add_f32_e32 v226, v226, v208
	v_add_f32_e32 v227, v227, v209
	v_add_f32_e32 v228, v228, v210
	v_add_f32_e32 v229, v229, v211
	s_waitcnt vmcnt(4)
	v_add_f32_e32 v226, v226, v212
	v_add_f32_e32 v227, v227, v213
	v_add_f32_e32 v228, v228, v214
	v_add_f32_e32 v229, v229, v215
	s_waitcnt vmcnt(3)
	v_add_f32_e32 v226, v226, v216
	v_add_f32_e32 v227, v227, v217
	v_add_f32_e32 v228, v228, v218
	v_add_f32_e32 v229, v229, v219
	s_waitcnt vmcnt(2)
; __device__ __forceinline__ float bf2f(u16 h) { return __uint_as_float(((unsigned)h) << 16); }
; __device__ __forceinline__ void phase_fixup(PP p, const int g_wid, const float alpha_in) {
;     ...
;       for (int ai = 0; ai < 2; ++ai)
; #pragma unroll
;         for (int m = 0; m < 4; ++m) {
;           const int q = ((ai * 2 + bj) * 4 + m) * 2 + n;
;           f32x4 s = pb[((long)pn * 32 + q) * 512];
; #pragma unroll
;           for (int ks = 1; ks < 11; ++ks) s += pb[((long)(ks * 4 + pn) * 32 + q) * 512];
;           const u16x4 ho = *reinterpret_cast<const u16x4*>(hbr + ai * 128 + m * 16);
;           float4 hv;
;           hv.x = bf2f(ho[0]) + alpha * s[0]; hv.y = bf2f(ho[1]) + alpha * s[1];
;           hv.z = bf2f(ho[2]) + alpha * s[2]; hv.w = bf2f(ho[3]) + alpha * s[3];
;           *reinterpret_cast<u16x4*>(hbr + ai * 128 + m * 16) = pack4(hv.x, hv.y, hv.z, hv.w);
;           sq += (hv.x * hv.x + hv.y * hv.y) + (hv.z * hv.z + hv.w * hv.w);
;         }
	v_add_f32_e32 v226, v226, v220
	v_add_f32_e32 v227, v227, v221
	v_add_f32_e32 v228, v228, v222
	v_add_f32_e32 v229, v229, v223
	s_mov_b64 s[8:9], 0xc000
	v_lshl_add_u64 v[172:173], v[166:167], 0, s[8:9]
	global_load_dwordx4 v[180:183], v[172:173], off
	v_lshl_add_u64 v[172:173], v[172:173], 0, s[18:19]
	global_load_dwordx4 v[184:187], v[172:173], off
	v_lshl_add_u64 v[172:173], v[172:173], 0, s[18:19]
	global_load_dwordx4 v[188:191], v[172:173], off
	v_lshl_add_u64 v[172:173], v[172:173], 0, s[18:19]
	global_load_dwordx4 v[192:195], v[172:173], off
	v_lshl_add_u64 v[172:173], v[172:173], 0, s[18:19]
	global_load_dwordx4 v[196:199], v[172:173], off
	v_lshl_add_u64 v[172:173], v[172:173], 0, s[18:19]
	global_load_dwordx4 v[200:203], v[172:173], off
	v_lshl_add_u64 v[172:173], v[172:173], 0, s[18:19]
	global_load_dwordx4 v[204:207], v[172:173], off
	v_lshl_add_u64 v[172:173], v[172:173], 0, s[18:19]
	global_load_dwordx4 v[208:211], v[172:173], off
	v_lshl_add_u64 v[172:173], v[172:173], 0, s[18:19]
	global_load_dwordx4 v[212:215], v[172:173], off
	v_lshl_add_u64 v[172:173], v[172:173], 0, s[18:19]
	global_load_dwordx4 v[216:219], v[172:173], off
	v_lshl_add_u64 v[172:173], v[172:173], 0, s[18:19]
	global_load_dwordx4 v[220:223], v[172:173], off
	global_load_dwordx2 v[238:239], v[168:169], off offset:96
	s_waitcnt vmcnt(13)
	v_lshlrev_b32_e32 v230, 16, v224
	v_and_b32_e32 v231, 0xffff0000, v224
	v_lshlrev_b32_e32 v232, 16, v225
	v_and_b32_e32 v233, 0xffff0000, v225
	v_fma_f32 v230, 0.5, v226, v230
	v_fma_f32 v231, 0.5, v227, v231
	v_fma_f32 v232, 0.5, v228, v232
	v_fma_f32 v233, 0.5, v229, v233
	v_cvt_pk_bf16_f32 v234, v230, v231
	v_cvt_pk_bf16_f32 v235, v232, v233
	global_store_dwordx2 v[168:169], v[234:235], off offset:64
	v_mul_f32_e32 v236, v231, v231
	v_fma_f32 v236, v230, v230, v236
	v_mul_f32_e32 v237, v233, v233
	v_fma_f32 v237, v232, v232, v237
	v_add_f32_e32 v236, v236, v237
	v_add_f32_e32 v170, v170, v236
	s_waitcnt vmcnt(11)
	v_add_f32_e32 v226, v180, v184
	v_add_f32_e32 v227, v181, v185
	v_add_f32_e32 v228, v182, v186
	v_add_f32_e32 v229, v183, v187
	s_waitcnt vmcnt(10)
	v_add_f32_e32 v226, v226, v188
	v_add_f32_e32 v227, v227, v189
	v_add_f32_e32 v228, v228, v190
	v_add_f32_e32 v229, v229, v191
	s_waitcnt vmcnt(9)
	v_add_f32_e32 v226, v226, v192
	v_add_f32_e32 v227, v227, v193
	v_add_f32_e32 v228, v228, v194
	v_add_f32_e32 v229, v229, v195
	s_waitcnt vmcnt(8)
	v_add_f32_e32 v226, v226, v196
	v_add_f32_e32 v227, v227, v197
	v_add_f32_e32 v228, v228, v198
	v_add_f32_e32 v229, v229, v199
	s_waitcnt vmcnt(7)
	v_add_f32_e32 v226, v226, v200
	v_add_f32_e32 v227, v227, v201
	v_add_f32_e32 v228, v228, v202
	v_add_f32_e32 v229, v229, v203
	s_waitcnt vmcnt(6)
	v_add_f32_e32 v226, v226, v204
	v_add_f32_e32 v227, v227, v205
	v_add_f32_e32 v228, v228, v206
	v_add_f32_e32 v229, v229, v207
	s_waitcnt vmcnt(5)
	v_add_f32_e32 v226, v226, v208
	v_add_f32_e32 v227, v227, v209
	v_add_f32_e32 v228, v228, v210
	v_add_f32_e32 v229, v229, v211
	s_waitcnt vmcnt(4)
	v_add_f32_e32 v226, v226, v212
	v_add_f32_e32 v227, v227, v213
	v_add_f32_e32 v228, v228, v214
	v_add_f32_e32 v229, v229, v215
	s_waitcnt vmcnt(3)
	v_add_f32_e32 v226, v226, v216
	v_add_f32_e32 v227, v227, v217
	v_add_f32_e32 v228, v228, v218
	v_add_f32_e32 v229, v229, v219
	s_waitcnt vmcnt(2)
	v_add_f32_e32 v226, v226, v220
	v_add_f32_e32 v227, v227, v221
	v_add_f32_e32 v228, v228, v222
	v_add_f32_e32 v229, v229, v223
	s_mov_b64 s[8:9], 0x20000
	v_lshl_add_u64 v[172:173], v[166:167], 0, s[8:9]
	global_load_dwordx4 v[180:183], v[172:173], off
	v_lshl_add_u64 v[172:173], v[172:173], 0, s[18:19]
	global_load_dwordx4 v[184:187], v[172:173], off
	v_lshl_add_u64 v[172:173], v[172:173], 0, s[18:19]
	global_load_dwordx4 v[188:191], v[172:173], off
	v_lshl_add_u64 v[172:173], v[172:173], 0, s[18:19]
	global_load_dwordx4 v[192:195], v[172:173], off
	v_lshl_add_u64 v[172:173], v[172:173], 0, s[18:19]
	global_load_dwordx4 v[196:199], v[172:173], off
	v_lshl_add_u64 v[172:173], v[172:173], 0, s[18:19]
	global_load_dwordx4 v[200:203], v[172:173], off
	v_lshl_add_u64 v[172:173], v[172:173], 0, s[18:19]
	global_load_dwordx4 v[204:207], v[172:173], off
	v_lshl_add_u64 v[172:173], v[172:173], 0, s[18:19]
	global_load_dwordx4 v[208:211], v[172:173], off
	v_lshl_add_u64 v[172:173], v[172:173], 0, s[18:19]
	global_load_dwordx4 v[212:215], v[172:173], off
	v_lshl_add_u64 v[172:173], v[172:173], 0, s[18:19]
	global_load_dwordx4 v[216:219], v[172:173], off
	v_lshl_add_u64 v[172:173], v[172:173], 0, s[18:19]
	global_load_dwordx4 v[220:223], v[172:173], off
	global_load_dwordx2 v[224:225], v[168:169], off offset:256
	s_waitcnt vmcnt(13)
	v_lshlrev_b32_e32 v230, 16, v238
	v_and_b32_e32 v231, 0xffff0000, v238
	v_lshlrev_b32_e32 v232, 16, v239
	v_and_b32_e32 v233, 0xffff0000, v239
	v_fma_f32 v230, 0.5, v226, v230
	v_fma_f32 v231, 0.5, v227, v231
	v_fma_f32 v232, 0.5, v228, v232
	v_fma_f32 v233, 0.5, v229, v233
	v_cvt_pk_bf16_f32 v234, v230, v231
	v_cvt_pk_bf16_f32 v235, v232, v233
	global_store_dwordx2 v[168:169], v[234:235], off offset:96
	v_mul_f32_e32 v236, v231, v231
	v_fma_f32 v236, v230, v230, v236
	v_mul_f32_e32 v237, v233, v233
	v_fma_f32 v237, v232, v232, v237
	v_add_f32_e32 v236, v236, v237
	v_add_f32_e32 v170, v170, v236
	s_waitcnt vmcnt(11)
	v_add_f32_e32 v226, v180, v184
	v_add_f32_e32 v227, v181, v185
	v_add_f32_e32 v228, v182, v186
	v_add_f32_e32 v229, v183, v187
	s_waitcnt vmcnt(10)
	v_add_f32_e32 v226, v226, v188
	v_add_f32_e32 v227, v227, v189
	v_add_f32_e32 v228, v228, v190
	v_add_f32_e32 v229, v229, v191
	s_waitcnt vmcnt(9)
; __device__ __forceinline__ float bf2f(u16 h) { return __uint_as_float(((unsigned)h) << 16); }
; __device__ __forceinline__ void phase_fixup(PP p, const int g_wid, const float alpha_in) {
;     ...
;       for (int ai = 0; ai < 2; ++ai)
; #pragma unroll
;         for (int m = 0; m < 4; ++m) {
;           const int q = ((ai * 2 + bj) * 4 + m) * 2 + n;
;           f32x4 s = pb[((long)pn * 32 + q) * 512];
; #pragma unroll
;           for (int ks = 1; ks < 11; ++ks) s += pb[((long)(ks * 4 + pn) * 32 + q) * 512];
;           const u16x4 ho = *reinterpret_cast<const u16x4*>(hbr + ai * 128 + m * 16);
;           float4 hv;
;           hv.x = bf2f(ho[0]) + alpha * s[0]; hv.y = bf2f(ho[1]) + alpha * s[1];
;           hv.z = bf2f(ho[2]) + alpha * s[2]; hv.w = bf2f(ho[3]) + alpha * s[3];
;           *reinterpret_cast<u16x4*>(hbr + ai * 128 + m * 16) = pack4(hv.x, hv.y, hv.z, hv.w);
;           sq += (hv.x * hv.x + hv.y * hv.y) + (hv.z * hv.z + hv.w * hv.w);
;         }
	v_add_f32_e32 v226, v226, v192
	v_add_f32_e32 v227, v227, v193
	v_add_f32_e32 v228, v228, v194
	v_add_f32_e32 v229, v229, v195
	s_waitcnt vmcnt(8)
	v_add_f32_e32 v226, v226, v196
	v_add_f32_e32 v227, v227, v197
	v_add_f32_e32 v228, v228, v198
	v_add_f32_e32 v229, v229, v199
	s_waitcnt vmcnt(7)
	v_add_f32_e32 v226, v226, v200
	v_add_f32_e32 v227, v227, v201
	v_add_f32_e32 v228, v228, v202
	v_add_f32_e32 v229, v229, v203
	s_waitcnt vmcnt(6)
	v_add_f32_e32 v226, v226, v204
	v_add_f32_e32 v227, v227, v205
	v_add_f32_e32 v228, v228, v206
	v_add_f32_e32 v229, v229, v207
	s_waitcnt vmcnt(5)
	v_add_f32_e32 v226, v226, v208
	v_add_f32_e32 v227, v227, v209
	v_add_f32_e32 v228, v228, v210
	v_add_f32_e32 v229, v229, v211
	s_waitcnt vmcnt(4)
	v_add_f32_e32 v226, v226, v212
	v_add_f32_e32 v227, v227, v213
	v_add_f32_e32 v228, v228, v214
	v_add_f32_e32 v229, v229, v215
	s_waitcnt vmcnt(3)
	v_add_f32_e32 v226, v226, v216
	v_add_f32_e32 v227, v227, v217
	v_add_f32_e32 v228, v228, v218
	v_add_f32_e32 v229, v229, v219
	s_waitcnt vmcnt(2)
	v_add_f32_e32 v226, v226, v220
	v_add_f32_e32 v227, v227, v221
	v_add_f32_e32 v228, v228, v222
	v_add_f32_e32 v229, v229, v223
	s_mov_b64 s[8:9], 0x24000
	v_lshl_add_u64 v[172:173], v[166:167], 0, s[8:9]
	global_load_dwordx4 v[180:183], v[172:173], off
	v_lshl_add_u64 v[172:173], v[172:173], 0, s[18:19]
	global_load_dwordx4 v[184:187], v[172:173], off
	v_lshl_add_u64 v[172:173], v[172:173], 0, s[18:19]
	global_load_dwordx4 v[188:191], v[172:173], off
	v_lshl_add_u64 v[172:173], v[172:173], 0, s[18:19]
	global_load_dwordx4 v[192:195], v[172:173], off
	v_lshl_add_u64 v[172:173], v[172:173], 0, s[18:19]
	global_load_dwordx4 v[196:199], v[172:173], off
	v_lshl_add_u64 v[172:173], v[172:173], 0, s[18:19]
	global_load_dwordx4 v[200:203], v[172:173], off
	v_lshl_add_u64 v[172:173], v[172:173], 0, s[18:19]
	global_load_dwordx4 v[204:207], v[172:173], off
	v_lshl_add_u64 v[172:173], v[172:173], 0, s[18:19]
	global_load_dwordx4 v[208:211], v[172:173], off
	v_lshl_add_u64 v[172:173], v[172:173], 0, s[18:19]
	global_load_dwordx4 v[212:215], v[172:173], off
	v_lshl_add_u64 v[172:173], v[172:173], 0, s[18:19]
	global_load_dwordx4 v[216:219], v[172:173], off
	v_lshl_add_u64 v[172:173], v[172:173], 0, s[18:19]
	global_load_dwordx4 v[220:223], v[172:173], off
	global_load_dwordx2 v[238:239], v[168:169], off offset:288
	s_waitcnt vmcnt(13)
	v_lshlrev_b32_e32 v230, 16, v224
	v_and_b32_e32 v231, 0xffff0000, v224
	v_lshlrev_b32_e32 v232, 16, v225
	v_and_b32_e32 v233, 0xffff0000, v225
	v_fma_f32 v230, 0.5, v226, v230
	v_fma_f32 v231, 0.5, v227, v231
	v_fma_f32 v232, 0.5, v228, v232
	v_fma_f32 v233, 0.5, v229, v233
	v_cvt_pk_bf16_f32 v234, v230, v231
	v_cvt_pk_bf16_f32 v235, v232, v233
	global_store_dwordx2 v[168:169], v[234:235], off offset:256
	v_mul_f32_e32 v236, v231, v231
	v_fma_f32 v236, v230, v230, v236
	v_mul_f32_e32 v237, v233, v233
	v_fma_f32 v237, v232, v232, v237
	v_add_f32_e32 v236, v236, v237
	v_add_f32_e32 v170, v170, v236
	s_waitcnt vmcnt(11)
	v_add_f32_e32 v226, v180, v184
	v_add_f32_e32 v227, v181, v185
	v_add_f32_e32 v228, v182, v186
	v_add_f32_e32 v229, v183, v187
	s_waitcnt vmcnt(10)
	v_add_f32_e32 v226, v226, v188
	v_add_f32_e32 v227, v227, v189
	v_add_f32_e32 v228, v228, v190
	v_add_f32_e32 v229, v229, v191
	s_waitcnt vmcnt(9)
	v_add_f32_e32 v226, v226, v192
	v_add_f32_e32 v227, v227, v193
	v_add_f32_e32 v228, v228, v194
	v_add_f32_e32 v229, v229, v195
	s_waitcnt vmcnt(8)
	v_add_f32_e32 v226, v226, v196
	v_add_f32_e32 v227, v227, v197
	v_add_f32_e32 v228, v228, v198
	v_add_f32_e32 v229, v229, v199
	s_waitcnt vmcnt(7)
	v_add_f32_e32 v226, v226, v200
	v_add_f32_e32 v227, v227, v201
	v_add_f32_e32 v228, v228, v202
	v_add_f32_e32 v229, v229, v203
	s_waitcnt vmcnt(6)
	v_add_f32_e32 v226, v226, v204
	v_add_f32_e32 v227, v227, v205
	v_add_f32_e32 v228, v228, v206
	v_add_f32_e32 v229, v229, v207
	s_waitcnt vmcnt(5)
	v_add_f32_e32 v226, v226, v208
	v_add_f32_e32 v227, v227, v209
	v_add_f32_e32 v228, v228, v210
	v_add_f32_e32 v229, v229, v211
	s_waitcnt vmcnt(4)
	v_add_f32_e32 v226, v226, v212
	v_add_f32_e32 v227, v227, v213
	v_add_f32_e32 v228, v228, v214
	v_add_f32_e32 v229, v229, v215
	s_waitcnt vmcnt(3)
	v_add_f32_e32 v226, v226, v216
	v_add_f32_e32 v227, v227, v217
	v_add_f32_e32 v228, v228, v218
	v_add_f32_e32 v229, v229, v219
	s_waitcnt vmcnt(2)
	v_add_f32_e32 v226, v226, v220
	v_add_f32_e32 v227, v227, v221
	v_add_f32_e32 v228, v228, v222
	v_add_f32_e32 v229, v229, v223
	s_mov_b64 s[8:9], 0x28000
	v_lshl_add_u64 v[172:173], v[166:167], 0, s[8:9]
	global_load_dwordx4 v[180:183], v[172:173], off
	v_lshl_add_u64 v[172:173], v[172:173], 0, s[18:19]
	global_load_dwordx4 v[184:187], v[172:173], off
	v_lshl_add_u64 v[172:173], v[172:173], 0, s[18:19]
	global_load_dwordx4 v[188:191], v[172:173], off
	v_lshl_add_u64 v[172:173], v[172:173], 0, s[18:19]
	global_load_dwordx4 v[192:195], v[172:173], off
	v_lshl_add_u64 v[172:173], v[172:173], 0, s[18:19]
	global_load_dwordx4 v[196:199], v[172:173], off
	v_lshl_add_u64 v[172:173], v[172:173], 0, s[18:19]
	global_load_dwordx4 v[200:203], v[172:173], off
	v_lshl_add_u64 v[172:173], v[172:173], 0, s[18:19]
	global_load_dwordx4 v[204:207], v[172:173], off
	v_lshl_add_u64 v[172:173], v[172:173], 0, s[18:19]
	global_load_dwordx4 v[208:211], v[172:173], off
	v_lshl_add_u64 v[172:173], v[172:173], 0, s[18:19]
	global_load_dwordx4 v[212:215], v[172:173], off
	v_lshl_add_u64 v[172:173], v[172:173], 0, s[18:19]
	global_load_dwordx4 v[216:219], v[172:173], off
	v_lshl_add_u64 v[172:173], v[172:173], 0, s[18:19]
	global_load_dwordx4 v[220:223], v[172:173], off
	global_load_dwordx2 v[224:225], v[168:169], off offset:320
	s_waitcnt vmcnt(13)
; __device__ __forceinline__ float bf2f(u16 h) { return __uint_as_float(((unsigned)h) << 16); }
; __device__ __forceinline__ void phase_fixup(PP p, const int g_wid, const float alpha_in) {
;     ...
;           for (int ks = 1; ks < 11; ++ks) s += pb[((long)(ks * 4 + pn) * 32 + q) * 512];
;           const u16x4 ho = *reinterpret_cast<const u16x4*>(hbr + ai * 128 + m * 16);
;           float4 hv;
;           hv.x = bf2f(ho[0]) + alpha * s[0]; hv.y = bf2f(ho[1]) + alpha * s[1];
;           hv.z = bf2f(ho[2]) + alpha * s[2]; hv.w = bf2f(ho[3]) + alpha * s[3];
;           *reinterpret_cast<u16x4*>(hbr + ai * 128 + m * 16) = pack4(hv.x, hv.y, hv.z, hv.w);
;           sq += (hv.x * hv.x + hv.y * hv.y) + (hv.z * hv.z + hv.w * hv.w);
;         }
;     }
;     sq += __shfl_xor(sq, 16); sq += __shfl_xor(sq, 32);
;     if (ok && fq == 0) ssq[(long)row * 16 + pn * 4 + wr] = sq;
;   }
; }
	v_lshlrev_b32_e32 v230, 16, v238
	v_and_b32_e32 v231, 0xffff0000, v238
	v_lshlrev_b32_e32 v232, 16, v239
	v_and_b32_e32 v233, 0xffff0000, v239
	v_fma_f32 v230, 0.5, v226, v230
	v_fma_f32 v231, 0.5, v227, v231
	v_fma_f32 v232, 0.5, v228, v232
	v_fma_f32 v233, 0.5, v229, v233
	v_cvt_pk_bf16_f32 v234, v230, v231
	v_cvt_pk_bf16_f32 v235, v232, v233
	global_store_dwordx2 v[168:169], v[234:235], off offset:288
	v_mul_f32_e32 v236, v231, v231
	v_fma_f32 v236, v230, v230, v236
	v_mul_f32_e32 v237, v233, v233
	v_fma_f32 v237, v232, v232, v237
	v_add_f32_e32 v236, v236, v237
	v_add_f32_e32 v170, v170, v236
	s_waitcnt vmcnt(11)
	v_add_f32_e32 v226, v180, v184
	v_add_f32_e32 v227, v181, v185
	v_add_f32_e32 v228, v182, v186
	v_add_f32_e32 v229, v183, v187
	s_waitcnt vmcnt(10)
	v_add_f32_e32 v226, v226, v188
	v_add_f32_e32 v227, v227, v189
	v_add_f32_e32 v228, v228, v190
	v_add_f32_e32 v229, v229, v191
	s_waitcnt vmcnt(9)
	v_add_f32_e32 v226, v226, v192
	v_add_f32_e32 v227, v227, v193
	v_add_f32_e32 v228, v228, v194
	v_add_f32_e32 v229, v229, v195
	s_waitcnt vmcnt(8)
	v_add_f32_e32 v226, v226, v196
	v_add_f32_e32 v227, v227, v197
	v_add_f32_e32 v228, v228, v198
	v_add_f32_e32 v229, v229, v199
	s_waitcnt vmcnt(7)
	v_add_f32_e32 v226, v226, v200
	v_add_f32_e32 v227, v227, v201
	v_add_f32_e32 v228, v228, v202
	v_add_f32_e32 v229, v229, v203
	s_waitcnt vmcnt(6)
	v_add_f32_e32 v226, v226, v204
	v_add_f32_e32 v227, v227, v205
	v_add_f32_e32 v228, v228, v206
	v_add_f32_e32 v229, v229, v207
	s_waitcnt vmcnt(5)
	v_add_f32_e32 v226, v226, v208
	v_add_f32_e32 v227, v227, v209
	v_add_f32_e32 v228, v228, v210
	v_add_f32_e32 v229, v229, v211
	s_waitcnt vmcnt(4)
	v_add_f32_e32 v226, v226, v212
	v_add_f32_e32 v227, v227, v213
	v_add_f32_e32 v228, v228, v214
	v_add_f32_e32 v229, v229, v215
	s_waitcnt vmcnt(3)
	v_add_f32_e32 v226, v226, v216
	v_add_f32_e32 v227, v227, v217
	v_add_f32_e32 v228, v228, v218
	v_add_f32_e32 v229, v229, v219
	s_waitcnt vmcnt(2)
	v_add_f32_e32 v226, v226, v220
	v_add_f32_e32 v227, v227, v221
	v_add_f32_e32 v228, v228, v222
	v_add_f32_e32 v229, v229, v223
	s_mov_b64 s[8:9], 0x2c000
	v_lshl_add_u64 v[172:173], v[166:167], 0, s[8:9]
	global_load_dwordx4 v[180:183], v[172:173], off
	v_lshl_add_u64 v[172:173], v[172:173], 0, s[18:19]
	global_load_dwordx4 v[184:187], v[172:173], off
	v_lshl_add_u64 v[172:173], v[172:173], 0, s[18:19]
	global_load_dwordx4 v[188:191], v[172:173], off
	v_lshl_add_u64 v[172:173], v[172:173], 0, s[18:19]
	global_load_dwordx4 v[192:195], v[172:173], off
	v_lshl_add_u64 v[172:173], v[172:173], 0, s[18:19]
	global_load_dwordx4 v[196:199], v[172:173], off
	v_lshl_add_u64 v[172:173], v[172:173], 0, s[18:19]
	global_load_dwordx4 v[200:203], v[172:173], off
	v_lshl_add_u64 v[172:173], v[172:173], 0, s[18:19]
	global_load_dwordx4 v[204:207], v[172:173], off
	v_lshl_add_u64 v[172:173], v[172:173], 0, s[18:19]
	global_load_dwordx4 v[208:211], v[172:173], off
	v_lshl_add_u64 v[172:173], v[172:173], 0, s[18:19]
	global_load_dwordx4 v[212:215], v[172:173], off
	v_lshl_add_u64 v[172:173], v[172:173], 0, s[18:19]
	global_load_dwordx4 v[216:219], v[172:173], off
	v_lshl_add_u64 v[172:173], v[172:173], 0, s[18:19]
	global_load_dwordx4 v[220:223], v[172:173], off
	global_load_dwordx2 v[238:239], v[168:169], off offset:352
	s_waitcnt vmcnt(13)
	v_lshlrev_b32_e32 v230, 16, v224
	v_and_b32_e32 v231, 0xffff0000, v224
	v_lshlrev_b32_e32 v232, 16, v225
	v_and_b32_e32 v233, 0xffff0000, v225
	v_fma_f32 v230, 0.5, v226, v230
	v_fma_f32 v231, 0.5, v227, v231
	v_fma_f32 v232, 0.5, v228, v232
	v_fma_f32 v233, 0.5, v229, v233
	v_cvt_pk_bf16_f32 v234, v230, v231
	v_cvt_pk_bf16_f32 v235, v232, v233
	global_store_dwordx2 v[168:169], v[234:235], off offset:320
	v_mul_f32_e32 v236, v231, v231
	v_fma_f32 v236, v230, v230, v236
	v_mul_f32_e32 v237, v233, v233
	v_fma_f32 v237, v232, v232, v237
	v_add_f32_e32 v236, v236, v237
	v_add_f32_e32 v170, v170, v236
	s_waitcnt vmcnt(11)
	v_add_f32_e32 v226, v180, v184
	v_add_f32_e32 v227, v181, v185
	v_add_f32_e32 v228, v182, v186
	v_add_f32_e32 v229, v183, v187
	s_waitcnt vmcnt(10)
	v_add_f32_e32 v226, v226, v188
	v_add_f32_e32 v227, v227, v189
	v_add_f32_e32 v228, v228, v190
	v_add_f32_e32 v229, v229, v191
	s_waitcnt vmcnt(9)
	v_add_f32_e32 v226, v226, v192
	v_add_f32_e32 v227, v227, v193
	v_add_f32_e32 v228, v228, v194
	v_add_f32_e32 v229, v229, v195
	s_waitcnt vmcnt(8)
	v_add_f32_e32 v226, v226, v196
	v_add_f32_e32 v227, v227, v197
	v_add_f32_e32 v228, v228, v198
	v_add_f32_e32 v229, v229, v199
	s_waitcnt vmcnt(7)
	v_add_f32_e32 v226, v226, v200
	v_add_f32_e32 v227, v227, v201
	v_add_f32_e32 v228, v228, v202
	v_add_f32_e32 v229, v229, v203
	s_waitcnt vmcnt(6)
	v_add_f32_e32 v226, v226, v204
	v_add_f32_e32 v227, v227, v205
	v_add_f32_e32 v228, v228, v206
	v_add_f32_e32 v229, v229, v207
	s_waitcnt vmcnt(5)
	v_add_f32_e32 v226, v226, v208
	v_add_f32_e32 v227, v227, v209
	v_add_f32_e32 v228, v228, v210
	v_add_f32_e32 v229, v229, v211
	s_waitcnt vmcnt(4)
	v_add_f32_e32 v226, v226, v212
	v_add_f32_e32 v227, v227, v213
	v_add_f32_e32 v228, v228, v214
	v_add_f32_e32 v229, v229, v215
	s_waitcnt vmcnt(3)
	v_add_f32_e32 v226, v226, v216
	v_add_f32_e32 v227, v227, v217
	v_add_f32_e32 v228, v228, v218
	v_add_f32_e32 v229, v229, v219
	s_waitcnt vmcnt(2)
	v_add_f32_e32 v226, v226, v220
	v_add_f32_e32 v227, v227, v221
	v_add_f32_e32 v228, v228, v222
	v_add_f32_e32 v229, v229, v223
	s_waitcnt vmcnt(1)
	v_lshlrev_b32_e32 v230, 16, v238
	v_and_b32_e32 v231, 0xffff0000, v238
	v_lshlrev_b32_e32 v232, 16, v239
	v_and_b32_e32 v233, 0xffff0000, v239
	v_fma_f32 v230, 0.5, v226, v230
	v_fma_f32 v231, 0.5, v227, v231
	v_fma_f32 v232, 0.5, v228, v232
	v_fma_f32 v233, 0.5, v229, v233
	v_cvt_pk_bf16_f32 v234, v230, v231
	v_cvt_pk_bf16_f32 v235, v232, v233
	global_store_dwordx2 v[168:169], v[234:235], off offset:352
	v_mul_f32_e32 v236, v231, v231
	v_fma_f32 v236, v230, v230, v236
	v_mul_f32_e32 v237, v233, v233
	v_fma_f32 v237, v232, v232, v237
	v_add_f32_e32 v236, v236, v237
	v_add_f32_e32 v170, v170, v236
.Lfx0_skip:
	s_or_b64 exec, exec, s[16:17]
	v_xor_b32_e32 v171, 16, v160
	v_lshlrev_b32_e32 v171, 2, v171
	ds_bpermute_b32 v178, v171, v170
	s_waitcnt lgkmcnt(0)
	v_add_f32_e32 v170, v170, v178
	v_xor_b32_e32 v171, 32, v160
	v_lshlrev_b32_e32 v171, 2, v171
	ds_bpermute_b32 v178, v171, v170
	s_waitcnt lgkmcnt(0)
	v_add_f32_e32 v170, v170, v178
	v_cmp_eq_u32_e64 s[18:19], 0, v163
	v_cmp_gt_u32_e32 vcc, 0xc0a0, v164
	s_nop 1
	s_and_b64 vcc, vcc, s[18:19]
	s_and_saveexec_b64 s[16:17], vcc
	s_cbranch_execz .Lfx0_done
	v_lshlrev_b32_e32 v176, 6, v164
	s_lshl_b32 s2, s4, 4
	s_lshr_b32 s11, s7, 2
	s_lshl_b32 s11, s11, 2
	s_add_i32 s2, s2, s11
	v_add_u32_e32 v176, s2, v176
	v_mov_b32_e32 v177, 0
	v_lshl_add_u64 v[176:177], s[14:15], 0, v[176:177]
	global_store_dword v[176:177], v170, off
.Lfx0_done:
	s_or_b64 exec, exec, s[16:17]
.LBB0_329:
	s_mov_b64 s[2:3], 0

; __device__ __forceinline__ void phase_fixup(PP p, const int g_wid, const float alpha_in) {
;     ...
;   if (bid < 16) {
;     float alpha = alpha_in; asm volatile("" : "+v"(alpha));
;     const int pn = bid & 3, bj = (bid >> 2) & 1, n = bid >> 3;
;     const int wid = tid >> 6, lane = tid & 63, wr = wid >> 2, wc = wid & 3, fr = lane & 15, fq = lane >> 4;
;     const f32x4* pb = reinterpret_cast<const f32x4*>(p->X + X_PB) + tid;
;     float* ssq = p->ssq;
;     const unsigned foff = wr * 64 + fq * 4;
;     const int row = 192 * 256 + wc * 32 + fr + bj * 128 + n * 16;
;     const bool ok = row < NTOK;
;     float sq = 0.f;
;     if (ok) {
;       u16* hbr = p->hb + (long)row * 1024 + pn * 256 + foff;
; #pragma unroll
;       for (int ai = 0; ai < 2; ++ai)
; #pragma unroll
;         for (int m = 0; m < 4; ++m) {
;           const int q = ((ai * 2 + bj) * 4 + m) * 2 + n;
;           f32x4 s = pb[((long)pn * 32 + q) * 512];
; #pragma unroll
;           for (int ks = 1; ks < 11; ++ks) s += pb[((long)(ks * 4 + pn) * 32 + q) * 512];
; __global__ void __launch_bounds__(512, 2) mega(Params p_arg) {
;     ...
;     switch (k) {
;       case 0: if (l > 0) phase_fixup(p, g_wid, 0.5f); break;
;       case 1: case 13: phase_g1(p, g_wid); if (k == 1) { __syncthreads(); phase_conv_ffn(p, g_wid, l, 0, 2, 150); } break;
;       case 2: case 14: phase_resid<2816, 2816>(p, g_wid, p->X, p->W + 5767168L, 0.5f); __syncthreads();
;         if (k == 2) phase_conv_mix(p, g_wid, l, 44); else if (l < 3) phase_conv_ffn(p, g_wid, l + 1, 0, 1, 44);
;         break;
;       case 3: phase_fixup(p, g_wid, 0.5f); break;
.LBB0_560:
	s_and_b64 vcc, exec, s[2:3]
	s_cbranch_vccz .LBB0_568
	v_readlane_b32 s2, v254, 2
	s_lshl_b32 s2, s2, 6
	s_nop 0
	v_writelane_b32 v254, s2, 63
	s_nop 0
	v_readlane_b32 s2, v254, 53
	s_cmp_lt_i32 s2, 15
	s_cbranch_scc1 .LBB0_568
	s_mov_b32 s2, -1
	s_waitcnt lgkmcnt(0)
	v_mbcnt_lo_u32_b32 v0, s2, 0
	v_mbcnt_hi_u32_b32 v0, s2, v0
	v_readlane_b32 s2, v254, 63
	s_nop 1
	v_or_b32_e32 v2, s2, v0
	v_readlane_b32 s2, v254, 3
	s_cmp_gt_i32 s2, 15
	s_cbranch_scc1 .LBB0_568
	s_mov_b32 s3, s2
	s_and_b32 s4, s3, 3
	s_bfe_u32 s5, s3, 0x10002
	s_lshr_b32 s6, s3, 3
	v_readlane_b32 s7, v254, 2
	v_readlane_b32 s16, v254, 0
	v_readlane_b32 s17, v254, 1
	s_load_dwordx2 s[8:9], s[16:17], 0xd0
	s_load_dwordx2 s[12:13], s[16:17], 0xc8
	s_load_dwordx2 s[14:15], s[16:17], 0xe0
	v_mbcnt_lo_u32_b32 v160, -1, 0
	v_mbcnt_hi_u32_b32 v160, -1, v160
	s_lshl_b32 s2, s7, 6
	v_or_b32_e32 v161, s2, v160
	v_and_b32_e32 v162, 15, v160
	v_lshrrev_b32_e32 v163, 4, v160
	s_and_b32 s2, s7, 3
	s_lshl_b32 s2, s2, 5
	s_lshl_b32 s11, s5, 7
	s_add_i32 s2, s2, s11
	s_lshl_b32 s11, s6, 4
	s_add_i32 s2, s2, s11
	v_add_u32_e32 v164, s2, v162
	v_add_u32_e32 v164, 0xc000, v164
	s_lshl_b32 s2, s4, 5
	s_lshl_b32 s11, s5, 3
	s_add_i32 s2, s2, s11
	s_add_i32 s2, s2, s6
	s_lshl_b32 s2, s2, 13
	s_waitcnt lgkmcnt(0)
	s_add_u32 s8, s8, 0x10960000
	s_addc_u32 s9, s9, 0
	s_add_u32 s8, s8, s2
	s_addc_u32 s9, s9, 0
	v_lshlrev_b32_e32 v174, 4, v161
	v_mov_b32_e32 v175, 0
	v_lshl_add_u64 v[166:167], s[8:9], 0, v[174:175]
	s_lshr_b32 s2, s7, 2
	s_lshl_b32 s2, s2, 7
	s_lshl_b32 s11, s4, 9
	s_add_i32 s2, s2, s11
	v_lshl_add_u32 v176, v163, 3, s2
	v_lshlrev_b32_e32 v177, 11, v164
	v_add_u32_e32 v176, v176, v177
	v_mov_b32_e32 v177, 0
	v_lshl_add_u64 v[168:169], s[12:13], 0, v[176:177]
	v_mov_b32_e32 v170, 0
	v_cmp_gt_u32_e32 vcc, 0xc0a0, v164
	s_and_saveexec_b64 s[16:17], vcc
	s_cbranch_execz .Lfx1_skip
	s_mov_b64 s[18:19], 0x100000
	v_mov_b64_e32 v[172:173], v[166:167]
	global_load_dwordx4 v[180:183], v[172:173], off
	v_lshl_add_u64 v[172:173], v[172:173], 0, s[18:19]
	global_load_dwordx4 v[184:187], v[172:173], off
	v_lshl_add_u64 v[172:173], v[172:173], 0, s[18:19]
	global_load_dwordx4 v[188:191], v[172:173], off
	v_lshl_add_u64 v[172:173], v[172:173], 0, s[18:19]
	global_load_dwordx4 v[192:195], v[172:173], off
	v_lshl_add_u64 v[172:173], v[172:173], 0, s[18:19]
	global_load_dwordx4 v[196:199], v[172:173], off
	v_lshl_add_u64 v[172:173], v[172:173], 0, s[18:19]
	global_load_dwordx4 v[200:203], v[172:173], off
	v_lshl_add_u64 v[172:173], v[172:173], 0, s[18:19]
	global_load_dwordx4 v[204:207], v[172:173], off
	v_lshl_add_u64 v[172:173], v[172:173], 0, s[18:19]
	global_load_dwordx4 v[208:211], v[172:173], off
	v_lshl_add_u64 v[172:173], v[172:173], 0, s[18:19]
	global_load_dwordx4 v[212:215], v[172:173], off
	v_lshl_add_u64 v[172:173], v[172:173], 0, s[18:19]
	global_load_dwordx4 v[216:219], v[172:173], off
	v_lshl_add_u64 v[172:173], v[172:173], 0, s[18:19]
	global_load_dwordx4 v[220:223], v[172:173], off
	global_load_dwordx2 v[224:225], v[168:169], off
	s_waitcnt vmcnt(10)
	v_add_f32_e32 v226, v180, v184
	v_add_f32_e32 v227, v181, v185
	v_add_f32_e32 v228, v182, v186
	v_add_f32_e32 v229, v183, v187
	s_waitcnt vmcnt(9)
	v_add_f32_e32 v226, v226, v188
	v_add_f32_e32 v227, v227, v189
	v_add_f32_e32 v228, v228, v190
	v_add_f32_e32 v229, v229, v191
	s_waitcnt vmcnt(8)
	v_add_f32_e32 v226, v226, v192
	v_add_f32_e32 v227, v227, v193
	v_add_f32_e32 v228, v228, v194
	v_add_f32_e32 v229, v229, v195
	s_waitcnt vmcnt(7)
	v_add_f32_e32 v226, v226, v196
	v_add_f32_e32 v227, v227, v197
	v_add_f32_e32 v228, v228, v198
	v_add_f32_e32 v229, v229, v199
	s_waitcnt vmcnt(6)
	v_add_f32_e32 v226, v226, v200
	v_add_f32_e32 v227, v227, v201
	v_add_f32_e32 v228, v228, v202
	v_add_f32_e32 v229, v229, v203
	s_waitcnt vmcnt(5)
	v_add_f32_e32 v226, v226, v204
	v_add_f32_e32 v227, v227, v205
	v_add_f32_e32 v228, v228, v206
	v_add_f32_e32 v229, v229, v207
	s_waitcnt vmcnt(4)
	v_add_f32_e32 v226, v226, v208
	v_add_f32_e32 v227, v227, v209
	v_add_f32_e32 v228, v228, v210
	v_add_f32_e32 v229, v229, v211
	s_waitcnt vmcnt(3)
	v_add_f32_e32 v226, v226, v212
	v_add_f32_e32 v227, v227, v213
	v_add_f32_e32 v228, v228, v214
	v_add_f32_e32 v229, v229, v215
	s_waitcnt vmcnt(2)
	v_add_f32_e32 v226, v226, v216
	v_add_f32_e32 v227, v227, v217
	v_add_f32_e32 v228, v228, v218
	v_add_f32_e32 v229, v229, v219
	s_waitcnt vmcnt(1)
	v_add_f32_e32 v226, v226, v220
	v_add_f32_e32 v227, v227, v221
	v_add_f32_e32 v228, v228, v222
	v_add_f32_e32 v229, v229, v223
	s_mov_b64 s[8:9], 0x4000
	v_lshl_add_u64 v[172:173], v[166:167], 0, s[8:9]
	global_load_dwordx4 v[180:183], v[172:173], off
	v_lshl_add_u64 v[172:173], v[172:173], 0, s[18:19]
	global_load_dwordx4 v[184:187], v[172:173], off
	v_lshl_add_u64 v[172:173], v[172:173], 0, s[18:19]
	global_load_dwordx4 v[188:191], v[172:173], off
	v_lshl_add_u64 v[172:173], v[172:173], 0, s[18:19]
	global_load_dwordx4 v[192:195], v[172:173], off
	v_lshl_add_u64 v[172:173], v[172:173], 0, s[18:19]
	global_load_dwordx4 v[196:199], v[172:173], off
	v_lshl_add_u64 v[172:173], v[172:173], 0, s[18:19]
	global_load_dwordx4 v[200:203], v[172:173], off
	v_lshl_add_u64 v[172:173], v[172:173], 0, s[18:19]
	global_load_dwordx4 v[204:207], v[172:173], off
	v_lshl_add_u64 v[172:173], v[172:173], 0, s[18:19]
	global_load_dwordx4 v[208:211], v[172:173], off
	v_lshl_add_u64 v[172:173], v[172:173], 0, s[18:19]
	global_load_dwordx4 v[212:215], v[172:173], off
	v_lshl_add_u64 v[172:173], v[172:173], 0, s[18:19]
	global_load_dwordx4 v[216:219], v[172:173], off
	v_lshl_add_u64 v[172:173], v[172:173], 0, s[18:19]
	global_load_dwordx4 v[220:223], v[172:173], off
	global_load_dwordx2 v[238:239], v[168:169], off offset:32
	s_waitcnt vmcnt(12)
; __device__ __forceinline__ float bf2f(u16 h) { return __uint_as_float(((unsigned)h) << 16); }
; __device__ __forceinline__ void phase_fixup(PP p, const int g_wid, const float alpha_in) {
;     ...
;       for (int ai = 0; ai < 2; ++ai)
; #pragma unroll
;         for (int m = 0; m < 4; ++m) {
;           const int q = ((ai * 2 + bj) * 4 + m) * 2 + n;
;           f32x4 s = pb[((long)pn * 32 + q) * 512];
; #pragma unroll
;           for (int ks = 1; ks < 11; ++ks) s += pb[((long)(ks * 4 + pn) * 32 + q) * 512];
;           const u16x4 ho = *reinterpret_cast<const u16x4*>(hbr + ai * 128 + m * 16);
;           float4 hv;
;           hv.x = bf2f(ho[0]) + alpha * s[0]; hv.y = bf2f(ho[1]) + alpha * s[1];
;           hv.z = bf2f(ho[2]) + alpha * s[2]; hv.w = bf2f(ho[3]) + alpha * s[3];
;           *reinterpret_cast<u16x4*>(hbr + ai * 128 + m * 16) = pack4(hv.x, hv.y, hv.z, hv.w);
;           sq += (hv.x * hv.x + hv.y * hv.y) + (hv.z * hv.z + hv.w * hv.w);
;         }
	v_lshlrev_b32_e32 v230, 16, v224
	v_and_b32_e32 v231, 0xffff0000, v224
	v_lshlrev_b32_e32 v232, 16, v225
	v_and_b32_e32 v233, 0xffff0000, v225
	v_fma_f32 v230, 0.5, v226, v230
	v_fma_f32 v231, 0.5, v227, v231
	v_fma_f32 v232, 0.5, v228, v232
	v_fma_f32 v233, 0.5, v229, v233
	v_cvt_pk_bf16_f32 v234, v230, v231
	v_cvt_pk_bf16_f32 v235, v232, v233
	global_store_dwordx2 v[168:169], v[234:235], off
	v_mul_f32_e32 v236, v231, v231
	v_fma_f32 v236, v230, v230, v236
	v_mul_f32_e32 v237, v233, v233
	v_fma_f32 v237, v232, v232, v237
	v_add_f32_e32 v236, v236, v237
	v_add_f32_e32 v170, v170, v236
	s_waitcnt vmcnt(11)
	v_add_f32_e32 v226, v180, v184
	v_add_f32_e32 v227, v181, v185
	v_add_f32_e32 v228, v182, v186
	v_add_f32_e32 v229, v183, v187
	s_waitcnt vmcnt(10)
	v_add_f32_e32 v226, v226, v188
	v_add_f32_e32 v227, v227, v189
	v_add_f32_e32 v228, v228, v190
	v_add_f32_e32 v229, v229, v191
	s_waitcnt vmcnt(9)
	v_add_f32_e32 v226, v226, v192
	v_add_f32_e32 v227, v227, v193
	v_add_f32_e32 v228, v228, v194
	v_add_f32_e32 v229, v229, v195
	s_waitcnt vmcnt(8)
	v_add_f32_e32 v226, v226, v196
	v_add_f32_e32 v227, v227, v197
	v_add_f32_e32 v228, v228, v198
	v_add_f32_e32 v229, v229, v199
	s_waitcnt vmcnt(7)
	v_add_f32_e32 v226, v226, v200
	v_add_f32_e32 v227, v227, v201
	v_add_f32_e32 v228, v228, v202
	v_add_f32_e32 v229, v229, v203
	s_waitcnt vmcnt(6)
	v_add_f32_e32 v226, v226, v204
	v_add_f32_e32 v227, v227, v205
	v_add_f32_e32 v228, v228, v206
	v_add_f32_e32 v229, v229, v207
	s_waitcnt vmcnt(5)
	v_add_f32_e32 v226, v226, v208
	v_add_f32_e32 v227, v227, v209
	v_add_f32_e32 v228, v228, v210
	v_add_f32_e32 v229, v229, v211
	s_waitcnt vmcnt(4)
	v_add_f32_e32 v226, v226, v212
	v_add_f32_e32 v227, v227, v213
	v_add_f32_e32 v228, v228, v214
	v_add_f32_e32 v229, v229, v215
	s_waitcnt vmcnt(3)
	v_add_f32_e32 v226, v226, v216
	v_add_f32_e32 v227, v227, v217
	v_add_f32_e32 v228, v228, v218
	v_add_f32_e32 v229, v229, v219
	s_waitcnt vmcnt(2)
	v_add_f32_e32 v226, v226, v220
	v_add_f32_e32 v227, v227, v221
	v_add_f32_e32 v228, v228, v222
	v_add_f32_e32 v229, v229, v223
	s_mov_b64 s[8:9], 0x8000
	v_lshl_add_u64 v[172:173], v[166:167], 0, s[8:9]
	global_load_dwordx4 v[180:183], v[172:173], off
	v_lshl_add_u64 v[172:173], v[172:173], 0, s[18:19]
	global_load_dwordx4 v[184:187], v[172:173], off
	v_lshl_add_u64 v[172:173], v[172:173], 0, s[18:19]
	global_load_dwordx4 v[188:191], v[172:173], off
	v_lshl_add_u64 v[172:173], v[172:173], 0, s[18:19]
	global_load_dwordx4 v[192:195], v[172:173], off
	v_lshl_add_u64 v[172:173], v[172:173], 0, s[18:19]
	global_load_dwordx4 v[196:199], v[172:173], off
	v_lshl_add_u64 v[172:173], v[172:173], 0, s[18:19]
	global_load_dwordx4 v[200:203], v[172:173], off
	v_lshl_add_u64 v[172:173], v[172:173], 0, s[18:19]
	global_load_dwordx4 v[204:207], v[172:173], off
	v_lshl_add_u64 v[172:173], v[172:173], 0, s[18:19]
	global_load_dwordx4 v[208:211], v[172:173], off
	v_lshl_add_u64 v[172:173], v[172:173], 0, s[18:19]
	global_load_dwordx4 v[212:215], v[172:173], off
	v_lshl_add_u64 v[172:173], v[172:173], 0, s[18:19]
	global_load_dwordx4 v[216:219], v[172:173], off
	v_lshl_add_u64 v[172:173], v[172:173], 0, s[18:19]
	global_load_dwordx4 v[220:223], v[172:173], off
	global_load_dwordx2 v[224:225], v[168:169], off offset:64
	s_waitcnt vmcnt(13)
	v_lshlrev_b32_e32 v230, 16, v238
	v_and_b32_e32 v231, 0xffff0000, v238
	v_lshlrev_b32_e32 v232, 16, v239
	v_and_b32_e32 v233, 0xffff0000, v239
	v_fma_f32 v230, 0.5, v226, v230
	v_fma_f32 v231, 0.5, v227, v231
	v_fma_f32 v232, 0.5, v228, v232
	v_fma_f32 v233, 0.5, v229, v233
	v_cvt_pk_bf16_f32 v234, v230, v231
	v_cvt_pk_bf16_f32 v235, v232, v233
	global_store_dwordx2 v[168:169], v[234:235], off offset:32
	v_mul_f32_e32 v236, v231, v231
	v_fma_f32 v236, v230, v230, v236
	v_mul_f32_e32 v237, v233, v233
	v_fma_f32 v237, v232, v232, v237
	v_add_f32_e32 v236, v236, v237
	v_add_f32_e32 v170, v170, v236
	s_waitcnt vmcnt(11)
	v_add_f32_e32 v226, v180, v184
	v_add_f32_e32 v227, v181, v185
	v_add_f32_e32 v228, v182, v186
	v_add_f32_e32 v229, v183, v187
	s_waitcnt vmcnt(10)
	v_add_f32_e32 v226, v226, v188
	v_add_f32_e32 v227, v227, v189
	v_add_f32_e32 v228, v228, v190
	v_add_f32_e32 v229, v229, v191
	s_waitcnt vmcnt(9)
	v_add_f32_e32 v226, v226, v192
	v_add_f32_e32 v227, v227, v193
	v_add_f32_e32 v228, v228, v194
	v_add_f32_e32 v229, v229, v195
	s_waitcnt vmcnt(8)
	v_add_f32_e32 v226, v226, v196
	v_add_f32_e32 v227, v227, v197
	v_add_f32_e32 v228, v228, v198
	v_add_f32_e32 v229, v229, v199
	s_waitcnt vmcnt(7)
	v_add_f32_e32 v226, v226, v200
	v_add_f32_e32 v227, v227, v201
	v_add_f32_e32 v228, v228, v202
	v_add_f32_e32 v229, v229, v203
	s_waitcnt vmcnt(6)
	v_add_f32_e32 v226, v226, v204
	v_add_f32_e32 v227, v227, v205
	v_add_f32_e32 v228, v228, v206
	v_add_f32_e32 v229, v229, v207
	s_waitcnt vmcnt(5)
	v_add_f32_e32 v226, v226, v208
	v_add_f32_e32 v227, v227, v209
	v_add_f32_e32 v228, v228, v210
	v_add_f32_e32 v229, v229, v211
	s_waitcnt vmcnt(4)
	v_add_f32_e32 v226, v226, v212
	v_add_f32_e32 v227, v227, v213
	v_add_f32_e32 v228, v228, v214
	v_add_f32_e32 v229, v229, v215
	s_waitcnt vmcnt(3)
	v_add_f32_e32 v226, v226, v216
	v_add_f32_e32 v227, v227, v217
	v_add_f32_e32 v228, v228, v218
	v_add_f32_e32 v229, v229, v219
	s_waitcnt vmcnt(2)
; __device__ __forceinline__ float bf2f(u16 h) { return __uint_as_float(((unsigned)h) << 16); }
; __device__ __forceinline__ void phase_fixup(PP p, const int g_wid, const float alpha_in) {
;     ...
;       for (int ai = 0; ai < 2; ++ai)
; #pragma unroll
;         for (int m = 0; m < 4; ++m) {
;           const int q = ((ai * 2 + bj) * 4 + m) * 2 + n;
;           f32x4 s = pb[((long)pn * 32 + q) * 512];
; #pragma unroll
;           for (int ks = 1; ks < 11; ++ks) s += pb[((long)(ks * 4 + pn) * 32 + q) * 512];
;           const u16x4 ho = *reinterpret_cast<const u16x4*>(hbr + ai * 128 + m * 16);
;           float4 hv;
;           hv.x = bf2f(ho[0]) + alpha * s[0]; hv.y = bf2f(ho[1]) + alpha * s[1];
;           hv.z = bf2f(ho[2]) + alpha * s[2]; hv.w = bf2f(ho[3]) + alpha * s[3];
;           *reinterpret_cast<u16x4*>(hbr + ai * 128 + m * 16) = pack4(hv.x, hv.y, hv.z, hv.w);
;           sq += (hv.x * hv.x + hv.y * hv.y) + (hv.z * hv.z + hv.w * hv.w);
;         }
	v_add_f32_e32 v226, v226, v220
	v_add_f32_e32 v227, v227, v221
	v_add_f32_e32 v228, v228, v222
	v_add_f32_e32 v229, v229, v223
	s_mov_b64 s[8:9], 0xc000
	v_lshl_add_u64 v[172:173], v[166:167], 0, s[8:9]
	global_load_dwordx4 v[180:183], v[172:173], off
	v_lshl_add_u64 v[172:173], v[172:173], 0, s[18:19]
	global_load_dwordx4 v[184:187], v[172:173], off
	v_lshl_add_u64 v[172:173], v[172:173], 0, s[18:19]
	global_load_dwordx4 v[188:191], v[172:173], off
	v_lshl_add_u64 v[172:173], v[172:173], 0, s[18:19]
	global_load_dwordx4 v[192:195], v[172:173], off
	v_lshl_add_u64 v[172:173], v[172:173], 0, s[18:19]
	global_load_dwordx4 v[196:199], v[172:173], off
	v_lshl_add_u64 v[172:173], v[172:173], 0, s[18:19]
	global_load_dwordx4 v[200:203], v[172:173], off
	v_lshl_add_u64 v[172:173], v[172:173], 0, s[18:19]
	global_load_dwordx4 v[204:207], v[172:173], off
	v_lshl_add_u64 v[172:173], v[172:173], 0, s[18:19]
	global_load_dwordx4 v[208:211], v[172:173], off
	v_lshl_add_u64 v[172:173], v[172:173], 0, s[18:19]
	global_load_dwordx4 v[212:215], v[172:173], off
	v_lshl_add_u64 v[172:173], v[172:173], 0, s[18:19]
	global_load_dwordx4 v[216:219], v[172:173], off
	v_lshl_add_u64 v[172:173], v[172:173], 0, s[18:19]
	global_load_dwordx4 v[220:223], v[172:173], off
	global_load_dwordx2 v[238:239], v[168:169], off offset:96
	s_waitcnt vmcnt(13)
	v_lshlrev_b32_e32 v230, 16, v224
	v_and_b32_e32 v231, 0xffff0000, v224
	v_lshlrev_b32_e32 v232, 16, v225
	v_and_b32_e32 v233, 0xffff0000, v225
	v_fma_f32 v230, 0.5, v226, v230
	v_fma_f32 v231, 0.5, v227, v231
	v_fma_f32 v232, 0.5, v228, v232
	v_fma_f32 v233, 0.5, v229, v233
	v_cvt_pk_bf16_f32 v234, v230, v231
	v_cvt_pk_bf16_f32 v235, v232, v233
	global_store_dwordx2 v[168:169], v[234:235], off offset:64
	v_mul_f32_e32 v236, v231, v231
	v_fma_f32 v236, v230, v230, v236
	v_mul_f32_e32 v237, v233, v233
	v_fma_f32 v237, v232, v232, v237
	v_add_f32_e32 v236, v236, v237
	v_add_f32_e32 v170, v170, v236
	s_waitcnt vmcnt(11)
	v_add_f32_e32 v226, v180, v184
	v_add_f32_e32 v227, v181, v185
	v_add_f32_e32 v228, v182, v186
	v_add_f32_e32 v229, v183, v187
	s_waitcnt vmcnt(10)
	v_add_f32_e32 v226, v226, v188
	v_add_f32_e32 v227, v227, v189
	v_add_f32_e32 v228, v228, v190
	v_add_f32_e32 v229, v229, v191
	s_waitcnt vmcnt(9)
	v_add_f32_e32 v226, v226, v192
	v_add_f32_e32 v227, v227, v193
	v_add_f32_e32 v228, v228, v194
	v_add_f32_e32 v229, v229, v195
	s_waitcnt vmcnt(8)
	v_add_f32_e32 v226, v226, v196
	v_add_f32_e32 v227, v227, v197
	v_add_f32_e32 v228, v228, v198
	v_add_f32_e32 v229, v229, v199
	s_waitcnt vmcnt(7)
	v_add_f32_e32 v226, v226, v200
	v_add_f32_e32 v227, v227, v201
	v_add_f32_e32 v228, v228, v202
	v_add_f32_e32 v229, v229, v203
	s_waitcnt vmcnt(6)
	v_add_f32_e32 v226, v226, v204
	v_add_f32_e32 v227, v227, v205
	v_add_f32_e32 v228, v228, v206
	v_add_f32_e32 v229, v229, v207
	s_waitcnt vmcnt(5)
	v_add_f32_e32 v226, v226, v208
	v_add_f32_e32 v227, v227, v209
	v_add_f32_e32 v228, v228, v210
	v_add_f32_e32 v229, v229, v211
	s_waitcnt vmcnt(4)
	v_add_f32_e32 v226, v226, v212
	v_add_f32_e32 v227, v227, v213
	v_add_f32_e32 v228, v228, v214
	v_add_f32_e32 v229, v229, v215
	s_waitcnt vmcnt(3)
	v_add_f32_e32 v226, v226, v216
	v_add_f32_e32 v227, v227, v217
	v_add_f32_e32 v228, v228, v218
	v_add_f32_e32 v229, v229, v219
	s_waitcnt vmcnt(2)
	v_add_f32_e32 v226, v226, v220
	v_add_f32_e32 v227, v227, v221
	v_add_f32_e32 v228, v228, v222
	v_add_f32_e32 v229, v229, v223
	s_mov_b64 s[8:9], 0x20000
	v_lshl_add_u64 v[172:173], v[166:167], 0, s[8:9]
	global_load_dwordx4 v[180:183], v[172:173], off
	v_lshl_add_u64 v[172:173], v[172:173], 0, s[18:19]
	global_load_dwordx4 v[184:187], v[172:173], off
	v_lshl_add_u64 v[172:173], v[172:173], 0, s[18:19]
	global_load_dwordx4 v[188:191], v[172:173], off
	v_lshl_add_u64 v[172:173], v[172:173], 0, s[18:19]
	global_load_dwordx4 v[192:195], v[172:173], off
	v_lshl_add_u64 v[172:173], v[172:173], 0, s[18:19]
	global_load_dwordx4 v[196:199], v[172:173], off
	v_lshl_add_u64 v[172:173], v[172:173], 0, s[18:19]
	global_load_dwordx4 v[200:203], v[172:173], off
	v_lshl_add_u64 v[172:173], v[172:173], 0, s[18:19]
	global_load_dwordx4 v[204:207], v[172:173], off
	v_lshl_add_u64 v[172:173], v[172:173], 0, s[18:19]
	global_load_dwordx4 v[208:211], v[172:173], off
	v_lshl_add_u64 v[172:173], v[172:173], 0, s[18:19]
	global_load_dwordx4 v[212:215], v[172:173], off
	v_lshl_add_u64 v[172:173], v[172:173], 0, s[18:19]
	global_load_dwordx4 v[216:219], v[172:173], off
	v_lshl_add_u64 v[172:173], v[172:173], 0, s[18:19]
	global_load_dwordx4 v[220:223], v[172:173], off
	global_load_dwordx2 v[224:225], v[168:169], off offset:256
	s_waitcnt vmcnt(13)
	v_lshlrev_b32_e32 v230, 16, v238
	v_and_b32_e32 v231, 0xffff0000, v238
	v_lshlrev_b32_e32 v232, 16, v239
	v_and_b32_e32 v233, 0xffff0000, v239
	v_fma_f32 v230, 0.5, v226, v230
	v_fma_f32 v231, 0.5, v227, v231
	v_fma_f32 v232, 0.5, v228, v232
	v_fma_f32 v233, 0.5, v229, v233
	v_cvt_pk_bf16_f32 v234, v230, v231
	v_cvt_pk_bf16_f32 v235, v232, v233
	global_store_dwordx2 v[168:169], v[234:235], off offset:96
	v_mul_f32_e32 v236, v231, v231
	v_fma_f32 v236, v230, v230, v236
	v_mul_f32_e32 v237, v233, v233
	v_fma_f32 v237, v232, v232, v237
	v_add_f32_e32 v236, v236, v237
	v_add_f32_e32 v170, v170, v236
	s_waitcnt vmcnt(11)
	v_add_f32_e32 v226, v180, v184
	v_add_f32_e32 v227, v181, v185
	v_add_f32_e32 v228, v182, v186
	v_add_f32_e32 v229, v183, v187
	s_waitcnt vmcnt(10)
	v_add_f32_e32 v226, v226, v188
	v_add_f32_e32 v227, v227, v189
	v_add_f32_e32 v228, v228, v190
	v_add_f32_e32 v229, v229, v191
	s_waitcnt vmcnt(9)
; __device__ __forceinline__ float bf2f(u16 h) { return __uint_as_float(((unsigned)h) << 16); }
; __device__ __forceinline__ void phase_fixup(PP p, const int g_wid, const float alpha_in) {
;     ...
;       for (int ai = 0; ai < 2; ++ai)
; #pragma unroll
;         for (int m = 0; m < 4; ++m) {
;           const int q = ((ai * 2 + bj) * 4 + m) * 2 + n;
;           f32x4 s = pb[((long)pn * 32 + q) * 512];
; #pragma unroll
;           for (int ks = 1; ks < 11; ++ks) s += pb[((long)(ks * 4 + pn) * 32 + q) * 512];
;           const u16x4 ho = *reinterpret_cast<const u16x4*>(hbr + ai * 128 + m * 16);
;           float4 hv;
;           hv.x = bf2f(ho[0]) + alpha * s[0]; hv.y = bf2f(ho[1]) + alpha * s[1];
;           hv.z = bf2f(ho[2]) + alpha * s[2]; hv.w = bf2f(ho[3]) + alpha * s[3];
;           *reinterpret_cast<u16x4*>(hbr + ai * 128 + m * 16) = pack4(hv.x, hv.y, hv.z, hv.w);
;           sq += (hv.x * hv.x + hv.y * hv.y) + (hv.z * hv.z + hv.w * hv.w);
;         }
	v_add_f32_e32 v226, v226, v192
	v_add_f32_e32 v227, v227, v193
	v_add_f32_e32 v228, v228, v194
	v_add_f32_e32 v229, v229, v195
	s_waitcnt vmcnt(8)
	v_add_f32_e32 v226, v226, v196
	v_add_f32_e32 v227, v227, v197
	v_add_f32_e32 v228, v228, v198
	v_add_f32_e32 v229, v229, v199
	s_waitcnt vmcnt(7)
	v_add_f32_e32 v226, v226, v200
	v_add_f32_e32 v227, v227, v201
	v_add_f32_e32 v228, v228, v202
	v_add_f32_e32 v229, v229, v203
	s_waitcnt vmcnt(6)
	v_add_f32_e32 v226, v226, v204
	v_add_f32_e32 v227, v227, v205
	v_add_f32_e32 v228, v228, v206
	v_add_f32_e32 v229, v229, v207
	s_waitcnt vmcnt(5)
	v_add_f32_e32 v226, v226, v208
	v_add_f32_e32 v227, v227, v209
	v_add_f32_e32 v228, v228, v210
	v_add_f32_e32 v229, v229, v211
	s_waitcnt vmcnt(4)
	v_add_f32_e32 v226, v226, v212
	v_add_f32_e32 v227, v227, v213
	v_add_f32_e32 v228, v228, v214
	v_add_f32_e32 v229, v229, v215
	s_waitcnt vmcnt(3)
	v_add_f32_e32 v226, v226, v216
	v_add_f32_e32 v227, v227, v217
	v_add_f32_e32 v228, v228, v218
	v_add_f32_e32 v229, v229, v219
	s_waitcnt vmcnt(2)
	v_add_f32_e32 v226, v226, v220
	v_add_f32_e32 v227, v227, v221
	v_add_f32_e32 v228, v228, v222
	v_add_f32_e32 v229, v229, v223
	s_mov_b64 s[8:9], 0x24000
	v_lshl_add_u64 v[172:173], v[166:167], 0, s[8:9]
	global_load_dwordx4 v[180:183], v[172:173], off
	v_lshl_add_u64 v[172:173], v[172:173], 0, s[18:19]
	global_load_dwordx4 v[184:187], v[172:173], off
	v_lshl_add_u64 v[172:173], v[172:173], 0, s[18:19]
	global_load_dwordx4 v[188:191], v[172:173], off
	v_lshl_add_u64 v[172:173], v[172:173], 0, s[18:19]
	global_load_dwordx4 v[192:195], v[172:173], off
	v_lshl_add_u64 v[172:173], v[172:173], 0, s[18:19]
	global_load_dwordx4 v[196:199], v[172:173], off
	v_lshl_add_u64 v[172:173], v[172:173], 0, s[18:19]
	global_load_dwordx4 v[200:203], v[172:173], off
	v_lshl_add_u64 v[172:173], v[172:173], 0, s[18:19]
	global_load_dwordx4 v[204:207], v[172:173], off
	v_lshl_add_u64 v[172:173], v[172:173], 0, s[18:19]
	global_load_dwordx4 v[208:211], v[172:173], off
	v_lshl_add_u64 v[172:173], v[172:173], 0, s[18:19]
	global_load_dwordx4 v[212:215], v[172:173], off
	v_lshl_add_u64 v[172:173], v[172:173], 0, s[18:19]
	global_load_dwordx4 v[216:219], v[172:173], off
	v_lshl_add_u64 v[172:173], v[172:173], 0, s[18:19]
	global_load_dwordx4 v[220:223], v[172:173], off
	global_load_dwordx2 v[238:239], v[168:169], off offset:288
	s_waitcnt vmcnt(13)
	v_lshlrev_b32_e32 v230, 16, v224
	v_and_b32_e32 v231, 0xffff0000, v224
	v_lshlrev_b32_e32 v232, 16, v225
	v_and_b32_e32 v233, 0xffff0000, v225
	v_fma_f32 v230, 0.5, v226, v230
	v_fma_f32 v231, 0.5, v227, v231
	v_fma_f32 v232, 0.5, v228, v232
	v_fma_f32 v233, 0.5, v229, v233
	v_cvt_pk_bf16_f32 v234, v230, v231
	v_cvt_pk_bf16_f32 v235, v232, v233
	global_store_dwordx2 v[168:169], v[234:235], off offset:256
	v_mul_f32_e32 v236, v231, v231
	v_fma_f32 v236, v230, v230, v236
	v_mul_f32_e32 v237, v233, v233
	v_fma_f32 v237, v232, v232, v237
	v_add_f32_e32 v236, v236, v237
	v_add_f32_e32 v170, v170, v236
	s_waitcnt vmcnt(11)
	v_add_f32_e32 v226, v180, v184
	v_add_f32_e32 v227, v181, v185
	v_add_f32_e32 v228, v182, v186
	v_add_f32_e32 v229, v183, v187
	s_waitcnt vmcnt(10)
	v_add_f32_e32 v226, v226, v188
	v_add_f32_e32 v227, v227, v189
	v_add_f32_e32 v228, v228, v190
	v_add_f32_e32 v229, v229, v191
	s_waitcnt vmcnt(9)
	v_add_f32_e32 v226, v226, v192
	v_add_f32_e32 v227, v227, v193
	v_add_f32_e32 v228, v228, v194
	v_add_f32_e32 v229, v229, v195
	s_waitcnt vmcnt(8)
	v_add_f32_e32 v226, v226, v196
	v_add_f32_e32 v227, v227, v197
	v_add_f32_e32 v228, v228, v198
	v_add_f32_e32 v229, v229, v199
	s_waitcnt vmcnt(7)
	v_add_f32_e32 v226, v226, v200
	v_add_f32_e32 v227, v227, v201
	v_add_f32_e32 v228, v228, v202
	v_add_f32_e32 v229, v229, v203
	s_waitcnt vmcnt(6)
	v_add_f32_e32 v226, v226, v204
	v_add_f32_e32 v227, v227, v205
	v_add_f32_e32 v228, v228, v206
	v_add_f32_e32 v229, v229, v207
	s_waitcnt vmcnt(5)
	v_add_f32_e32 v226, v226, v208
	v_add_f32_e32 v227, v227, v209
	v_add_f32_e32 v228, v228, v210
	v_add_f32_e32 v229, v229, v211
	s_waitcnt vmcnt(4)
	v_add_f32_e32 v226, v226, v212
	v_add_f32_e32 v227, v227, v213
	v_add_f32_e32 v228, v228, v214
	v_add_f32_e32 v229, v229, v215
	s_waitcnt vmcnt(3)
	v_add_f32_e32 v226, v226, v216
	v_add_f32_e32 v227, v227, v217
	v_add_f32_e32 v228, v228, v218
	v_add_f32_e32 v229, v229, v219
	s_waitcnt vmcnt(2)
	v_add_f32_e32 v226, v226, v220
	v_add_f32_e32 v227, v227, v221
	v_add_f32_e32 v228, v228, v222
	v_add_f32_e32 v229, v229, v223
	s_mov_b64 s[8:9], 0x28000
	v_lshl_add_u64 v[172:173], v[166:167], 0, s[8:9]
	global_load_dwordx4 v[180:183], v[172:173], off
	v_lshl_add_u64 v[172:173], v[172:173], 0, s[18:19]
	global_load_dwordx4 v[184:187], v[172:173], off
	v_lshl_add_u64 v[172:173], v[172:173], 0, s[18:19]
	global_load_dwordx4 v[188:191], v[172:173], off
	v_lshl_add_u64 v[172:173], v[172:173], 0, s[18:19]
	global_load_dwordx4 v[192:195], v[172:173], off
	v_lshl_add_u64 v[172:173], v[172:173], 0, s[18:19]
	global_load_dwordx4 v[196:199], v[172:173], off
	v_lshl_add_u64 v[172:173], v[172:173], 0, s[18:19]
	global_load_dwordx4 v[200:203], v[172:173], off
	v_lshl_add_u64 v[172:173], v[172:173], 0, s[18:19]
	global_load_dwordx4 v[204:207], v[172:173], off
	v_lshl_add_u64 v[172:173], v[172:173], 0, s[18:19]
	global_load_dwordx4 v[208:211], v[172:173], off
	v_lshl_add_u64 v[172:173], v[172:173], 0, s[18:19]
	global_load_dwordx4 v[212:215], v[172:173], off
	v_lshl_add_u64 v[172:173], v[172:173], 0, s[18:19]
	global_load_dwordx4 v[216:219], v[172:173], off
	v_lshl_add_u64 v[172:173], v[172:173], 0, s[18:19]
	global_load_dwordx4 v[220:223], v[172:173], off
	global_load_dwordx2 v[224:225], v[168:169], off offset:320
	s_waitcnt vmcnt(13)
; __device__ __forceinline__ float bf2f(u16 h) { return __uint_as_float(((unsigned)h) << 16); }
; __device__ __forceinline__ void phase_fixup(PP p, const int g_wid, const float alpha_in) {
;     ...
;           for (int ks = 1; ks < 11; ++ks) s += pb[((long)(ks * 4 + pn) * 32 + q) * 512];
;           const u16x4 ho = *reinterpret_cast<const u16x4*>(hbr + ai * 128 + m * 16);
;           float4 hv;
;           hv.x = bf2f(ho[0]) + alpha * s[0]; hv.y = bf2f(ho[1]) + alpha * s[1];
;           hv.z = bf2f(ho[2]) + alpha * s[2]; hv.w = bf2f(ho[3]) + alpha * s[3];
;           *reinterpret_cast<u16x4*>(hbr + ai * 128 + m * 16) = pack4(hv.x, hv.y, hv.z, hv.w);
;           sq += (hv.x * hv.x + hv.y * hv.y) + (hv.z * hv.z + hv.w * hv.w);
;         }
	v_lshlrev_b32_e32 v230, 16, v238
	v_and_b32_e32 v231, 0xffff0000, v238
	v_lshlrev_b32_e32 v232, 16, v239
	v_and_b32_e32 v233, 0xffff0000, v239
	v_fma_f32 v230, 0.5, v226, v230
	v_fma_f32 v231, 0.5, v227, v231
	v_fma_f32 v232, 0.5, v228, v232
	v_fma_f32 v233, 0.5, v229, v233
	v_cvt_pk_bf16_f32 v234, v230, v231
	v_cvt_pk_bf16_f32 v235, v232, v233
	global_store_dwordx2 v[168:169], v[234:235], off offset:288
	v_mul_f32_e32 v236, v231, v231
	v_fma_f32 v236, v230, v230, v236
	v_mul_f32_e32 v237, v233, v233
	v_fma_f32 v237, v232, v232, v237
	v_add_f32_e32 v236, v236, v237
	v_add_f32_e32 v170, v170, v236
	s_waitcnt vmcnt(11)
	v_add_f32_e32 v226, v180, v184
	v_add_f32_e32 v227, v181, v185
	v_add_f32_e32 v228, v182, v186
	v_add_f32_e32 v229, v183, v187
	s_waitcnt vmcnt(10)
	v_add_f32_e32 v226, v226, v188
	v_add_f32_e32 v227, v227, v189
	v_add_f32_e32 v228, v228, v190
	v_add_f32_e32 v229, v229, v191
	s_waitcnt vmcnt(9)
	v_add_f32_e32 v226, v226, v192
	v_add_f32_e32 v227, v227, v193
	v_add_f32_e32 v228, v228, v194
	v_add_f32_e32 v229, v229, v195
	s_waitcnt vmcnt(8)
	v_add_f32_e32 v226, v226, v196
	v_add_f32_e32 v227, v227, v197
	v_add_f32_e32 v228, v228, v198
	v_add_f32_e32 v229, v229, v199
	s_waitcnt vmcnt(7)
	v_add_f32_e32 v226, v226, v200
	v_add_f32_e32 v227, v227, v201
	v_add_f32_e32 v228, v228, v202
	v_add_f32_e32 v229, v229, v203
	s_waitcnt vmcnt(6)
	v_add_f32_e32 v226, v226, v204
	v_add_f32_e32 v227, v227, v205
	v_add_f32_e32 v228, v228, v206
	v_add_f32_e32 v229, v229, v207
	s_waitcnt vmcnt(5)
	v_add_f32_e32 v226, v226, v208
	v_add_f32_e32 v227, v227, v209
	v_add_f32_e32 v228, v228, v210
	v_add_f32_e32 v229, v229, v211
	s_waitcnt vmcnt(4)
	v_add_f32_e32 v226, v226, v212
	v_add_f32_e32 v227, v227, v213
	v_add_f32_e32 v228, v228, v214
	v_add_f32_e32 v229, v229, v215
	s_waitcnt vmcnt(3)
	v_add_f32_e32 v226, v226, v216
	v_add_f32_e32 v227, v227, v217
	v_add_f32_e32 v228, v228, v218
	v_add_f32_e32 v229, v229, v219
	s_waitcnt vmcnt(2)
	v_add_f32_e32 v226, v226, v220
	v_add_f32_e32 v227, v227, v221
	v_add_f32_e32 v228, v228, v222
	v_add_f32_e32 v229, v229, v223
	s_mov_b64 s[8:9], 0x2c000
	v_lshl_add_u64 v[172:173], v[166:167], 0, s[8:9]
	global_load_dwordx4 v[180:183], v[172:173], off
	v_lshl_add_u64 v[172:173], v[172:173], 0, s[18:19]
	global_load_dwordx4 v[184:187], v[172:173], off
	v_lshl_add_u64 v[172:173], v[172:173], 0, s[18:19]
	global_load_dwordx4 v[188:191], v[172:173], off
	v_lshl_add_u64 v[172:173], v[172:173], 0, s[18:19]
	global_load_dwordx4 v[192:195], v[172:173], off
	v_lshl_add_u64 v[172:173], v[172:173], 0, s[18:19]
	global_load_dwordx4 v[196:199], v[172:173], off
	v_lshl_add_u64 v[172:173], v[172:173], 0, s[18:19]
	global_load_dwordx4 v[200:203], v[172:173], off
	v_lshl_add_u64 v[172:173], v[172:173], 0, s[18:19]
	global_load_dwordx4 v[204:207], v[172:173], off
	v_lshl_add_u64 v[172:173], v[172:173], 0, s[18:19]
	global_load_dwordx4 v[208:211], v[172:173], off
	v_lshl_add_u64 v[172:173], v[172:173], 0, s[18:19]
	global_load_dwordx4 v[212:215], v[172:173], off
	v_lshl_add_u64 v[172:173], v[172:173], 0, s[18:19]
	global_load_dwordx4 v[216:219], v[172:173], off
	v_lshl_add_u64 v[172:173], v[172:173], 0, s[18:19]
	global_load_dwordx4 v[220:223], v[172:173], off
	global_load_dwordx2 v[238:239], v[168:169], off offset:352
	s_waitcnt vmcnt(13)
	v_lshlrev_b32_e32 v230, 16, v224
	v_and_b32_e32 v231, 0xffff0000, v224
	v_lshlrev_b32_e32 v232, 16, v225
	v_and_b32_e32 v233, 0xffff0000, v225
	v_fma_f32 v230, 0.5, v226, v230
	v_fma_f32 v231, 0.5, v227, v231
	v_fma_f32 v232, 0.5, v228, v232
	v_fma_f32 v233, 0.5, v229, v233
	v_cvt_pk_bf16_f32 v234, v230, v231
	v_cvt_pk_bf16_f32 v235, v232, v233
	global_store_dwordx2 v[168:169], v[234:235], off offset:320
	v_mul_f32_e32 v236, v231, v231
	v_fma_f32 v236, v230, v230, v236
	v_mul_f32_e32 v237, v233, v233
	v_fma_f32 v237, v232, v232, v237
	v_add_f32_e32 v236, v236, v237
	v_add_f32_e32 v170, v170, v236
	s_waitcnt vmcnt(11)
	v_add_f32_e32 v226, v180, v184
	v_add_f32_e32 v227, v181, v185
	v_add_f32_e32 v228, v182, v186
	v_add_f32_e32 v229, v183, v187
	s_waitcnt vmcnt(10)
	v_add_f32_e32 v226, v226, v188
	v_add_f32_e32 v227, v227, v189
	v_add_f32_e32 v228, v228, v190
	v_add_f32_e32 v229, v229, v191
	s_waitcnt vmcnt(9)
	v_add_f32_e32 v226, v226, v192
	v_add_f32_e32 v227, v227, v193
	v_add_f32_e32 v228, v228, v194
	v_add_f32_e32 v229, v229, v195
	s_waitcnt vmcnt(8)
	v_add_f32_e32 v226, v226, v196
	v_add_f32_e32 v227, v227, v197
	v_add_f32_e32 v228, v228, v198
	v_add_f32_e32 v229, v229, v199
	s_waitcnt vmcnt(7)
	v_add_f32_e32 v226, v226, v200
	v_add_f32_e32 v227, v227, v201
	v_add_f32_e32 v228, v228, v202
	v_add_f32_e32 v229, v229, v203
	s_waitcnt vmcnt(6)
	v_add_f32_e32 v226, v226, v204
	v_add_f32_e32 v227, v227, v205
	v_add_f32_e32 v228, v228, v206
	v_add_f32_e32 v229, v229, v207
	s_waitcnt vmcnt(5)
	v_add_f32_e32 v226, v226, v208
	v_add_f32_e32 v227, v227, v209
	v_add_f32_e32 v228, v228, v210
	v_add_f32_e32 v229, v229, v211
	s_waitcnt vmcnt(4)
	v_add_f32_e32 v226, v226, v212
	v_add_f32_e32 v227, v227, v213
	v_add_f32_e32 v228, v228, v214
	v_add_f32_e32 v229, v229, v215
	s_waitcnt vmcnt(3)
	v_add_f32_e32 v226, v226, v216
	v_add_f32_e32 v227, v227, v217
	v_add_f32_e32 v228, v228, v218
	v_add_f32_e32 v229, v229, v219
	s_waitcnt vmcnt(2)
	v_add_f32_e32 v226, v226, v220
	v_add_f32_e32 v227, v227, v221
	v_add_f32_e32 v228, v228, v222
	v_add_f32_e32 v229, v229, v223
	s_waitcnt vmcnt(1)
	v_lshlrev_b32_e32 v230, 16, v238
	v_and_b32_e32 v231, 0xffff0000, v238
	v_lshlrev_b32_e32 v232, 16, v239
	v_and_b32_e32 v233, 0xffff0000, v239
	v_fma_f32 v230, 0.5, v226, v230
	v_fma_f32 v231, 0.5, v227, v231
	v_fma_f32 v232, 0.5, v228, v232
	v_fma_f32 v233, 0.5, v229, v233
	v_cvt_pk_bf16_f32 v234, v230, v231
	v_cvt_pk_bf16_f32 v235, v232, v233
	global_store_dwordx2 v[168:169], v[234:235], off offset:352
	v_mul_f32_e32 v236, v231, v231
	v_fma_f32 v236, v230, v230, v236
	v_mul_f32_e32 v237, v233, v233
	v_fma_f32 v237, v232, v232, v237
	v_add_f32_e32 v236, v236, v237
	v_add_f32_e32 v170, v170, v236

; __device__ __forceinline__ unsigned xb_add(unsigned* p, unsigned v) { return __hip_atomic_fetch_add(p, v, __ATOMIC_RELAXED, __HIP_MEMORY_SCOPE_AGENT); }
; __device__ __forceinline__ void phase_fixup(PP p, const int g_wid, const float alpha_in) {
;     ...
;     sq += __shfl_xor(sq, 16); sq += __shfl_xor(sq, 32);
;     if (ok && fq == 0) ssq[(long)row * 16 + pn * 4 + wr] = sq;
; __device__ __forceinline__ void xcd_barrier(const XcdBarrier& b, int tid, const unsigned gen) {
;   asm volatile("s_waitcnt vmcnt(0)" ::: "memory");
;   __syncthreads();
;   if (tid == 0) {
;     unsigned* bar = b.bar;
;     __builtin_amdgcn_s_waitcnt(0);
;     const unsigned old = xb_add(&bar[XB_XSUB(b.x)], 1u);
.Lfx1_done:
	s_or_b64 exec, exec, s[16:17]
.LBB0_568:
	s_mov_b32 s2, -1
	v_add_u32_e32 v49, 1, v158
	s_waitcnt lgkmcnt(0)
	v_mbcnt_lo_u32_b32 v0, s2, 0
	v_mbcnt_hi_u32_b32 v0, s2, v0
	v_readlane_b32 s2, v254, 63
	s_nop 1
	v_or_b32_e32 v0, s2, v0
	s_waitcnt vmcnt(0)
	s_waitcnt vmcnt(0)
	v_cmp_ne_u32_e32 vcc, 0, v0
	s_barrier
	s_and_saveexec_b64 s[2:3], vcc
	s_xor_b64 s[2:3], exec, s[2:3]
	v_add_u32_e32 v49, 1, v158
	s_andn2_saveexec_b64 s[2:3], s[2:3]
	s_cbranch_execz .LBB0_608
	s_mov_b64 s[4:5], exec
	v_mbcnt_lo_u32_b32 v0, s4, 0
	v_mbcnt_hi_u32_b32 v0, s5, v0
	v_cmp_eq_u32_e32 vcc, 0, v0
	s_waitcnt vmcnt(0) expcnt(0) lgkmcnt(0)
	s_and_saveexec_b64 s[6:7], vcc
	s_cbranch_execz .LBB0_573
	s_bcnt1_i32_b64 s4, s[4:5]
	v_mov_b32_e32 v2, s4
	v_readlane_b32 s4, v254, 17
	v_readlane_b32 s5, v254, 18
	s_nop 4
	global_atomic_add v2, v1, v2, s[4:5] sc0

; __device__ __forceinline__ void phase_fixup(PP p, const int g_wid, const float alpha_in) {
;     ...
;   if (bid < 16) {
;     float alpha = alpha_in; asm volatile("" : "+v"(alpha));
;     const int pn = bid & 3, bj = (bid >> 2) & 1, n = bid >> 3;
;     const int wid = tid >> 6, lane = tid & 63, wr = wid >> 2, wc = wid & 3, fr = lane & 15, fq = lane >> 4;
;     const f32x4* pb = reinterpret_cast<const f32x4*>(p->X + X_PB) + tid;
;     float* ssq = p->ssq;
;     const unsigned foff = wr * 64 + fq * 4;
;     const int row = 192 * 256 + wc * 32 + fr + bj * 128 + n * 16;
;     const bool ok = row < NTOK;
;     float sq = 0.f;
;     if (ok) {
;       u16* hbr = p->hb + (long)row * 1024 + pn * 256 + foff;
; #pragma unroll
;       for (int ai = 0; ai < 2; ++ai)
; #pragma unroll
;         for (int m = 0; m < 4; ++m) {
;           const int q = ((ai * 2 + bj) * 4 + m) * 2 + n;
;           f32x4 s = pb[((long)pn * 32 + q) * 512];
; #pragma unroll
;           for (int ks = 1; ks < 11; ++ks) s += pb[((long)(ks * 4 + pn) * 32 + q) * 512];
; __global__ void __launch_bounds__(512, 2) mega(Params p_arg) {
;     ...
;   phase_fixup(p, g_wid, 0.5f);
.LBB0_611:
	s_mov_b32 s0, -1
	s_mov_b32 s10, -1
	v_mbcnt_lo_u32_b32 v0, s0, 0
	v_mbcnt_hi_u32_b32 v0, s0, v0
	v_or_b32_e32 v0, s33, v0
	v_readlane_b32 s0, v254, 3
	s_cmp_gt_i32 s0, 15
	s_cbranch_scc1 .LBB0_617
	s_mov_b32 s3, s0
	s_and_b32 s4, s3, 3
	s_bfe_u32 s5, s3, 0x10002
	s_lshr_b32 s6, s3, 3
	v_readlane_b32 s7, v254, 2
	v_readlane_b32 s16, v254, 0
	v_readlane_b32 s17, v254, 1
	s_load_dwordx2 s[8:9], s[16:17], 0xd0
	s_load_dwordx2 s[12:13], s[16:17], 0xc8
	s_load_dwordx2 s[14:15], s[16:17], 0xe0
	v_mbcnt_lo_u32_b32 v160, -1, 0
	v_mbcnt_hi_u32_b32 v160, -1, v160
	s_lshl_b32 s2, s7, 6
	v_or_b32_e32 v161, s2, v160
	v_and_b32_e32 v162, 15, v160
	v_lshrrev_b32_e32 v163, 4, v160
	s_and_b32 s2, s7, 3
	s_lshl_b32 s2, s2, 5
	s_lshl_b32 s11, s5, 7
	s_add_i32 s2, s2, s11
	s_lshl_b32 s11, s6, 4
	s_add_i32 s2, s2, s11
	v_add_u32_e32 v164, s2, v162
	v_add_u32_e32 v164, 0xc000, v164
	s_lshl_b32 s2, s4, 5
	s_lshl_b32 s11, s5, 3
	s_add_i32 s2, s2, s11
	s_add_i32 s2, s2, s6
	s_lshl_b32 s2, s2, 13
	s_waitcnt lgkmcnt(0)
	s_add_u32 s8, s8, 0x10960000
	s_addc_u32 s9, s9, 0
	s_add_u32 s8, s8, s2
	s_addc_u32 s9, s9, 0
	v_lshlrev_b32_e32 v174, 4, v161
	v_mov_b32_e32 v175, 0
	v_lshl_add_u64 v[166:167], s[8:9], 0, v[174:175]
	s_lshr_b32 s2, s7, 2
	s_lshl_b32 s2, s2, 7
	s_lshl_b32 s11, s4, 9
	s_add_i32 s2, s2, s11
	v_lshl_add_u32 v176, v163, 3, s2
	v_lshlrev_b32_e32 v177, 11, v164
	v_add_u32_e32 v176, v176, v177
	v_mov_b32_e32 v177, 0
	v_lshl_add_u64 v[168:169], s[12:13], 0, v[176:177]
	v_mov_b32_e32 v170, 0
	v_cmp_gt_u32_e32 vcc, 0xc0a0, v164
	s_and_saveexec_b64 s[16:17], vcc
	s_cbranch_execz .Lfx2_skip
	s_mov_b64 s[18:19], 0x100000
	v_mov_b64_e32 v[172:173], v[166:167]
	global_load_dwordx4 v[180:183], v[172:173], off
	v_lshl_add_u64 v[172:173], v[172:173], 0, s[18:19]
	global_load_dwordx4 v[184:187], v[172:173], off
	v_lshl_add_u64 v[172:173], v[172:173], 0, s[18:19]
	global_load_dwordx4 v[188:191], v[172:173], off
	v_lshl_add_u64 v[172:173], v[172:173], 0, s[18:19]
	global_load_dwordx4 v[192:195], v[172:173], off
	v_lshl_add_u64 v[172:173], v[172:173], 0, s[18:19]
	global_load_dwordx4 v[196:199], v[172:173], off
	v_lshl_add_u64 v[172:173], v[172:173], 0, s[18:19]
	global_load_dwordx4 v[200:203], v[172:173], off
	v_lshl_add_u64 v[172:173], v[172:173], 0, s[18:19]
	global_load_dwordx4 v[204:207], v[172:173], off
	v_lshl_add_u64 v[172:173], v[172:173], 0, s[18:19]
	global_load_dwordx4 v[208:211], v[172:173], off
	v_lshl_add_u64 v[172:173], v[172:173], 0, s[18:19]
	global_load_dwordx4 v[212:215], v[172:173], off
	v_lshl_add_u64 v[172:173], v[172:173], 0, s[18:19]
	global_load_dwordx4 v[216:219], v[172:173], off
	v_lshl_add_u64 v[172:173], v[172:173], 0, s[18:19]
	global_load_dwordx4 v[220:223], v[172:173], off
	global_load_dwordx2 v[224:225], v[168:169], off
	s_waitcnt vmcnt(10)
	v_add_f32_e32 v226, v180, v184
	v_add_f32_e32 v227, v181, v185
	v_add_f32_e32 v228, v182, v186
	v_add_f32_e32 v229, v183, v187
	s_waitcnt vmcnt(9)
	v_add_f32_e32 v226, v226, v188
	v_add_f32_e32 v227, v227, v189
	v_add_f32_e32 v228, v228, v190
	v_add_f32_e32 v229, v229, v191
	s_waitcnt vmcnt(8)
	v_add_f32_e32 v226, v226, v192
	v_add_f32_e32 v227, v227, v193
	v_add_f32_e32 v228, v228, v194
	v_add_f32_e32 v229, v229, v195
	s_waitcnt vmcnt(7)
	v_add_f32_e32 v226, v226, v196
	v_add_f32_e32 v227, v227, v197
	v_add_f32_e32 v228, v228, v198
	v_add_f32_e32 v229, v229, v199
	s_waitcnt vmcnt(6)
	v_add_f32_e32 v226, v226, v200
	v_add_f32_e32 v227, v227, v201
	v_add_f32_e32 v228, v228, v202
	v_add_f32_e32 v229, v229, v203
	s_waitcnt vmcnt(5)
	v_add_f32_e32 v226, v226, v204
	v_add_f32_e32 v227, v227, v205
	v_add_f32_e32 v228, v228, v206
	v_add_f32_e32 v229, v229, v207
	s_waitcnt vmcnt(4)
	v_add_f32_e32 v226, v226, v208
	v_add_f32_e32 v227, v227, v209
	v_add_f32_e32 v228, v228, v210
	v_add_f32_e32 v229, v229, v211
	s_waitcnt vmcnt(3)
	v_add_f32_e32 v226, v226, v212
	v_add_f32_e32 v227, v227, v213
	v_add_f32_e32 v228, v228, v214
	v_add_f32_e32 v229, v229, v215
	s_waitcnt vmcnt(2)
	v_add_f32_e32 v226, v226, v216
	v_add_f32_e32 v227, v227, v217
	v_add_f32_e32 v228, v228, v218
	v_add_f32_e32 v229, v229, v219
	s_waitcnt vmcnt(1)
	v_add_f32_e32 v226, v226, v220
	v_add_f32_e32 v227, v227, v221
	v_add_f32_e32 v228, v228, v222
	v_add_f32_e32 v229, v229, v223
	s_mov_b64 s[8:9], 0x4000
	v_lshl_add_u64 v[172:173], v[166:167], 0, s[8:9]
	global_load_dwordx4 v[180:183], v[172:173], off
	v_lshl_add_u64 v[172:173], v[172:173], 0, s[18:19]
	global_load_dwordx4 v[184:187], v[172:173], off
	v_lshl_add_u64 v[172:173], v[172:173], 0, s[18:19]
	global_load_dwordx4 v[188:191], v[172:173], off
	v_lshl_add_u64 v[172:173], v[172:173], 0, s[18:19]
	global_load_dwordx4 v[192:195], v[172:173], off
	v_lshl_add_u64 v[172:173], v[172:173], 0, s[18:19]
	global_load_dwordx4 v[196:199], v[172:173], off
	v_lshl_add_u64 v[172:173], v[172:173], 0, s[18:19]
	global_load_dwordx4 v[200:203], v[172:173], off
	v_lshl_add_u64 v[172:173], v[172:173], 0, s[18:19]
	global_load_dwordx4 v[204:207], v[172:173], off
	v_lshl_add_u64 v[172:173], v[172:173], 0, s[18:19]
	global_load_dwordx4 v[208:211], v[172:173], off
	v_lshl_add_u64 v[172:173], v[172:173], 0, s[18:19]
	global_load_dwordx4 v[212:215], v[172:173], off
	v_lshl_add_u64 v[172:173], v[172:173], 0, s[18:19]
	global_load_dwordx4 v[216:219], v[172:173], off
	v_lshl_add_u64 v[172:173], v[172:173], 0, s[18:19]
	global_load_dwordx4 v[220:223], v[172:173], off
	global_load_dwordx2 v[238:239], v[168:169], off offset:32
	s_waitcnt vmcnt(12)
; __device__ __forceinline__ float bf2f(u16 h) { return __uint_as_float(((unsigned)h) << 16); }
; __device__ __forceinline__ void phase_fixup(PP p, const int g_wid, const float alpha_in) {
;     ...
;       for (int ai = 0; ai < 2; ++ai)
; #pragma unroll
;         for (int m = 0; m < 4; ++m) {
;           const int q = ((ai * 2 + bj) * 4 + m) * 2 + n;
;           f32x4 s = pb[((long)pn * 32 + q) * 512];
; #pragma unroll
;           for (int ks = 1; ks < 11; ++ks) s += pb[((long)(ks * 4 + pn) * 32 + q) * 512];
;           const u16x4 ho = *reinterpret_cast<const u16x4*>(hbr + ai * 128 + m * 16);
;           float4 hv;
;           hv.x = bf2f(ho[0]) + alpha * s[0]; hv.y = bf2f(ho[1]) + alpha * s[1];
;           hv.z = bf2f(ho[2]) + alpha * s[2]; hv.w = bf2f(ho[3]) + alpha * s[3];
;           *reinterpret_cast<u16x4*>(hbr + ai * 128 + m * 16) = pack4(hv.x, hv.y, hv.z, hv.w);
;           sq += (hv.x * hv.x + hv.y * hv.y) + (hv.z * hv.z + hv.w * hv.w);
;         }
	v_lshlrev_b32_e32 v230, 16, v224
	v_and_b32_e32 v231, 0xffff0000, v224
	v_lshlrev_b32_e32 v232, 16, v225
	v_and_b32_e32 v233, 0xffff0000, v225
	v_fma_f32 v230, 0.5, v226, v230
	v_fma_f32 v231, 0.5, v227, v231
	v_fma_f32 v232, 0.5, v228, v232
	v_fma_f32 v233, 0.5, v229, v233
	v_cvt_pk_bf16_f32 v234, v230, v231
	v_cvt_pk_bf16_f32 v235, v232, v233
	global_store_dwordx2 v[168:169], v[234:235], off
	v_mul_f32_e32 v236, v231, v231
	v_fma_f32 v236, v230, v230, v236
	v_mul_f32_e32 v237, v233, v233
	v_fma_f32 v237, v232, v232, v237
	v_add_f32_e32 v236, v236, v237
	v_add_f32_e32 v170, v170, v236
	s_waitcnt vmcnt(11)
	v_add_f32_e32 v226, v180, v184
	v_add_f32_e32 v227, v181, v185
	v_add_f32_e32 v228, v182, v186
	v_add_f32_e32 v229, v183, v187
	s_waitcnt vmcnt(10)
	v_add_f32_e32 v226, v226, v188
	v_add_f32_e32 v227, v227, v189
	v_add_f32_e32 v228, v228, v190
	v_add_f32_e32 v229, v229, v191
	s_waitcnt vmcnt(9)
	v_add_f32_e32 v226, v226, v192
	v_add_f32_e32 v227, v227, v193
	v_add_f32_e32 v228, v228, v194
	v_add_f32_e32 v229, v229, v195
	s_waitcnt vmcnt(8)
	v_add_f32_e32 v226, v226, v196
	v_add_f32_e32 v227, v227, v197
	v_add_f32_e32 v228, v228, v198
	v_add_f32_e32 v229, v229, v199
	s_waitcnt vmcnt(7)
	v_add_f32_e32 v226, v226, v200
	v_add_f32_e32 v227, v227, v201
	v_add_f32_e32 v228, v228, v202
	v_add_f32_e32 v229, v229, v203
	s_waitcnt vmcnt(6)
	v_add_f32_e32 v226, v226, v204
	v_add_f32_e32 v227, v227, v205
	v_add_f32_e32 v228, v228, v206
	v_add_f32_e32 v229, v229, v207
	s_waitcnt vmcnt(5)
	v_add_f32_e32 v226, v226, v208
	v_add_f32_e32 v227, v227, v209
	v_add_f32_e32 v228, v228, v210
	v_add_f32_e32 v229, v229, v211
	s_waitcnt vmcnt(4)
	v_add_f32_e32 v226, v226, v212
	v_add_f32_e32 v227, v227, v213
	v_add_f32_e32 v228, v228, v214
	v_add_f32_e32 v229, v229, v215
	s_waitcnt vmcnt(3)
	v_add_f32_e32 v226, v226, v216
	v_add_f32_e32 v227, v227, v217
	v_add_f32_e32 v228, v228, v218
	v_add_f32_e32 v229, v229, v219
	s_waitcnt vmcnt(2)
	v_add_f32_e32 v226, v226, v220
	v_add_f32_e32 v227, v227, v221
	v_add_f32_e32 v228, v228, v222
	v_add_f32_e32 v229, v229, v223
	s_mov_b64 s[8:9], 0x8000
	v_lshl_add_u64 v[172:173], v[166:167], 0, s[8:9]
	global_load_dwordx4 v[180:183], v[172:173], off
	v_lshl_add_u64 v[172:173], v[172:173], 0, s[18:19]
	global_load_dwordx4 v[184:187], v[172:173], off
	v_lshl_add_u64 v[172:173], v[172:173], 0, s[18:19]
	global_load_dwordx4 v[188:191], v[172:173], off
	v_lshl_add_u64 v[172:173], v[172:173], 0, s[18:19]
	global_load_dwordx4 v[192:195], v[172:173], off
	v_lshl_add_u64 v[172:173], v[172:173], 0, s[18:19]
	global_load_dwordx4 v[196:199], v[172:173], off
	v_lshl_add_u64 v[172:173], v[172:173], 0, s[18:19]
	global_load_dwordx4 v[200:203], v[172:173], off
	v_lshl_add_u64 v[172:173], v[172:173], 0, s[18:19]
	global_load_dwordx4 v[204:207], v[172:173], off
	v_lshl_add_u64 v[172:173], v[172:173], 0, s[18:19]
	global_load_dwordx4 v[208:211], v[172:173], off
	v_lshl_add_u64 v[172:173], v[172:173], 0, s[18:19]
	global_load_dwordx4 v[212:215], v[172:173], off
	v_lshl_add_u64 v[172:173], v[172:173], 0, s[18:19]
	global_load_dwordx4 v[216:219], v[172:173], off
	v_lshl_add_u64 v[172:173], v[172:173], 0, s[18:19]
	global_load_dwordx4 v[220:223], v[172:173], off
	global_load_dwordx2 v[224:225], v[168:169], off offset:64
	s_waitcnt vmcnt(13)
	v_lshlrev_b32_e32 v230, 16, v238
	v_and_b32_e32 v231, 0xffff0000, v238
	v_lshlrev_b32_e32 v232, 16, v239
	v_and_b32_e32 v233, 0xffff0000, v239
	v_fma_f32 v230, 0.5, v226, v230
	v_fma_f32 v231, 0.5, v227, v231
	v_fma_f32 v232, 0.5, v228, v232
	v_fma_f32 v233, 0.5, v229, v233
	v_cvt_pk_bf16_f32 v234, v230, v231
	v_cvt_pk_bf16_f32 v235, v232, v233
	global_store_dwordx2 v[168:169], v[234:235], off offset:32
	v_mul_f32_e32 v236, v231, v231
	v_fma_f32 v236, v230, v230, v236
	v_mul_f32_e32 v237, v233, v233
	v_fma_f32 v237, v232, v232, v237
	v_add_f32_e32 v236, v236, v237
	v_add_f32_e32 v170, v170, v236
	s_waitcnt vmcnt(11)
	v_add_f32_e32 v226, v180, v184
	v_add_f32_e32 v227, v181, v185
	v_add_f32_e32 v228, v182, v186
	v_add_f32_e32 v229, v183, v187
	s_waitcnt vmcnt(10)
	v_add_f32_e32 v226, v226, v188
	v_add_f32_e32 v227, v227, v189
	v_add_f32_e32 v228, v228, v190
	v_add_f32_e32 v229, v229, v191
	s_waitcnt vmcnt(9)
	v_add_f32_e32 v226, v226, v192
	v_add_f32_e32 v227, v227, v193
	v_add_f32_e32 v228, v228, v194
	v_add_f32_e32 v229, v229, v195
	s_waitcnt vmcnt(8)
	v_add_f32_e32 v226, v226, v196
	v_add_f32_e32 v227, v227, v197
	v_add_f32_e32 v228, v228, v198
	v_add_f32_e32 v229, v229, v199
	s_waitcnt vmcnt(7)
	v_add_f32_e32 v226, v226, v200
	v_add_f32_e32 v227, v227, v201
	v_add_f32_e32 v228, v228, v202
	v_add_f32_e32 v229, v229, v203
	s_waitcnt vmcnt(6)
	v_add_f32_e32 v226, v226, v204
	v_add_f32_e32 v227, v227, v205
	v_add_f32_e32 v228, v228, v206
	v_add_f32_e32 v229, v229, v207
	s_waitcnt vmcnt(5)
	v_add_f32_e32 v226, v226, v208
	v_add_f32_e32 v227, v227, v209
	v_add_f32_e32 v228, v228, v210
	v_add_f32_e32 v229, v229, v211
	s_waitcnt vmcnt(4)
	v_add_f32_e32 v226, v226, v212
	v_add_f32_e32 v227, v227, v213
	v_add_f32_e32 v228, v228, v214
	v_add_f32_e32 v229, v229, v215
	s_waitcnt vmcnt(3)
	v_add_f32_e32 v226, v226, v216
	v_add_f32_e32 v227, v227, v217
	v_add_f32_e32 v228, v228, v218
	v_add_f32_e32 v229, v229, v219
	s_waitcnt vmcnt(2)
; __device__ __forceinline__ float bf2f(u16 h) { return __uint_as_float(((unsigned)h) << 16); }
; __device__ __forceinline__ void phase_fixup(PP p, const int g_wid, const float alpha_in) {
;     ...
;       for (int ai = 0; ai < 2; ++ai)
; #pragma unroll
;         for (int m = 0; m < 4; ++m) {
;           const int q = ((ai * 2 + bj) * 4 + m) * 2 + n;
;           f32x4 s = pb[((long)pn * 32 + q) * 512];
; #pragma unroll
;           for (int ks = 1; ks < 11; ++ks) s += pb[((long)(ks * 4 + pn) * 32 + q) * 512];
;           const u16x4 ho = *reinterpret_cast<const u16x4*>(hbr + ai * 128 + m * 16);
;           float4 hv;
;           hv.x = bf2f(ho[0]) + alpha * s[0]; hv.y = bf2f(ho[1]) + alpha * s[1];
;           hv.z = bf2f(ho[2]) + alpha * s[2]; hv.w = bf2f(ho[3]) + alpha * s[3];
;           *reinterpret_cast<u16x4*>(hbr + ai * 128 + m * 16) = pack4(hv.x, hv.y, hv.z, hv.w);
;           sq += (hv.x * hv.x + hv.y * hv.y) + (hv.z * hv.z + hv.w * hv.w);
;         }
	v_add_f32_e32 v226, v226, v220
	v_add_f32_e32 v227, v227, v221
	v_add_f32_e32 v228, v228, v222
	v_add_f32_e32 v229, v229, v223
	s_mov_b64 s[8:9], 0xc000
	v_lshl_add_u64 v[172:173], v[166:167], 0, s[8:9]
	global_load_dwordx4 v[180:183], v[172:173], off
	v_lshl_add_u64 v[172:173], v[172:173], 0, s[18:19]
	global_load_dwordx4 v[184:187], v[172:173], off
	v_lshl_add_u64 v[172:173], v[172:173], 0, s[18:19]
	global_load_dwordx4 v[188:191], v[172:173], off
	v_lshl_add_u64 v[172:173], v[172:173], 0, s[18:19]
	global_load_dwordx4 v[192:195], v[172:173], off
	v_lshl_add_u64 v[172:173], v[172:173], 0, s[18:19]
	global_load_dwordx4 v[196:199], v[172:173], off
	v_lshl_add_u64 v[172:173], v[172:173], 0, s[18:19]
	global_load_dwordx4 v[200:203], v[172:173], off
	v_lshl_add_u64 v[172:173], v[172:173], 0, s[18:19]
	global_load_dwordx4 v[204:207], v[172:173], off
	v_lshl_add_u64 v[172:173], v[172:173], 0, s[18:19]
	global_load_dwordx4 v[208:211], v[172:173], off
	v_lshl_add_u64 v[172:173], v[172:173], 0, s[18:19]
	global_load_dwordx4 v[212:215], v[172:173], off
	v_lshl_add_u64 v[172:173], v[172:173], 0, s[18:19]
	global_load_dwordx4 v[216:219], v[172:173], off
	v_lshl_add_u64 v[172:173], v[172:173], 0, s[18:19]
	global_load_dwordx4 v[220:223], v[172:173], off
	global_load_dwordx2 v[238:239], v[168:169], off offset:96
	s_waitcnt vmcnt(13)
	v_lshlrev_b32_e32 v230, 16, v224
	v_and_b32_e32 v231, 0xffff0000, v224
	v_lshlrev_b32_e32 v232, 16, v225
	v_and_b32_e32 v233, 0xffff0000, v225
	v_fma_f32 v230, 0.5, v226, v230
	v_fma_f32 v231, 0.5, v227, v231
	v_fma_f32 v232, 0.5, v228, v232
	v_fma_f32 v233, 0.5, v229, v233
	v_cvt_pk_bf16_f32 v234, v230, v231
	v_cvt_pk_bf16_f32 v235, v232, v233
	global_store_dwordx2 v[168:169], v[234:235], off offset:64
	v_mul_f32_e32 v236, v231, v231
	v_fma_f32 v236, v230, v230, v236
	v_mul_f32_e32 v237, v233, v233
	v_fma_f32 v237, v232, v232, v237
	v_add_f32_e32 v236, v236, v237
	v_add_f32_e32 v170, v170, v236
	s_waitcnt vmcnt(11)
	v_add_f32_e32 v226, v180, v184
	v_add_f32_e32 v227, v181, v185
	v_add_f32_e32 v228, v182, v186
	v_add_f32_e32 v229, v183, v187
	s_waitcnt vmcnt(10)
	v_add_f32_e32 v226, v226, v188
	v_add_f32_e32 v227, v227, v189
	v_add_f32_e32 v228, v228, v190
	v_add_f32_e32 v229, v229, v191
	s_waitcnt vmcnt(9)
	v_add_f32_e32 v226, v226, v192
	v_add_f32_e32 v227, v227, v193
	v_add_f32_e32 v228, v228, v194
	v_add_f32_e32 v229, v229, v195
	s_waitcnt vmcnt(8)
	v_add_f32_e32 v226, v226, v196
	v_add_f32_e32 v227, v227, v197
	v_add_f32_e32 v228, v228, v198
	v_add_f32_e32 v229, v229, v199
	s_waitcnt vmcnt(7)
	v_add_f32_e32 v226, v226, v200
	v_add_f32_e32 v227, v227, v201
	v_add_f32_e32 v228, v228, v202
	v_add_f32_e32 v229, v229, v203
	s_waitcnt vmcnt(6)
	v_add_f32_e32 v226, v226, v204
	v_add_f32_e32 v227, v227, v205
	v_add_f32_e32 v228, v228, v206
	v_add_f32_e32 v229, v229, v207
	s_waitcnt vmcnt(5)
	v_add_f32_e32 v226, v226, v208
	v_add_f32_e32 v227, v227, v209
	v_add_f32_e32 v228, v228, v210
	v_add_f32_e32 v229, v229, v211
	s_waitcnt vmcnt(4)
	v_add_f32_e32 v226, v226, v212
	v_add_f32_e32 v227, v227, v213
	v_add_f32_e32 v228, v228, v214
	v_add_f32_e32 v229, v229, v215
	s_waitcnt vmcnt(3)
	v_add_f32_e32 v226, v226, v216
	v_add_f32_e32 v227, v227, v217
	v_add_f32_e32 v228, v228, v218
	v_add_f32_e32 v229, v229, v219
	s_waitcnt vmcnt(2)
	v_add_f32_e32 v226, v226, v220
	v_add_f32_e32 v227, v227, v221
	v_add_f32_e32 v228, v228, v222
	v_add_f32_e32 v229, v229, v223
	s_mov_b64 s[8:9], 0x20000
	v_lshl_add_u64 v[172:173], v[166:167], 0, s[8:9]
	global_load_dwordx4 v[180:183], v[172:173], off
	v_lshl_add_u64 v[172:173], v[172:173], 0, s[18:19]
	global_load_dwordx4 v[184:187], v[172:173], off
	v_lshl_add_u64 v[172:173], v[172:173], 0, s[18:19]
	global_load_dwordx4 v[188:191], v[172:173], off
	v_lshl_add_u64 v[172:173], v[172:173], 0, s[18:19]
	global_load_dwordx4 v[192:195], v[172:173], off
	v_lshl_add_u64 v[172:173], v[172:173], 0, s[18:19]
	global_load_dwordx4 v[196:199], v[172:173], off
	v_lshl_add_u64 v[172:173], v[172:173], 0, s[18:19]
	global_load_dwordx4 v[200:203], v[172:173], off
	v_lshl_add_u64 v[172:173], v[172:173], 0, s[18:19]
	global_load_dwordx4 v[204:207], v[172:173], off
	v_lshl_add_u64 v[172:173], v[172:173], 0, s[18:19]
	global_load_dwordx4 v[208:211], v[172:173], off
	v_lshl_add_u64 v[172:173], v[172:173], 0, s[18:19]
	global_load_dwordx4 v[212:215], v[172:173], off
	v_lshl_add_u64 v[172:173], v[172:173], 0, s[18:19]
	global_load_dwordx4 v[216:219], v[172:173], off
	v_lshl_add_u64 v[172:173], v[172:173], 0, s[18:19]
	global_load_dwordx4 v[220:223], v[172:173], off
	global_load_dwordx2 v[224:225], v[168:169], off offset:256
	s_waitcnt vmcnt(13)
	v_lshlrev_b32_e32 v230, 16, v238
	v_and_b32_e32 v231, 0xffff0000, v238
	v_lshlrev_b32_e32 v232, 16, v239
	v_and_b32_e32 v233, 0xffff0000, v239
	v_fma_f32 v230, 0.5, v226, v230
	v_fma_f32 v231, 0.5, v227, v231
	v_fma_f32 v232, 0.5, v228, v232
	v_fma_f32 v233, 0.5, v229, v233
	v_cvt_pk_bf16_f32 v234, v230, v231
	v_cvt_pk_bf16_f32 v235, v232, v233
	global_store_dwordx2 v[168:169], v[234:235], off offset:96
	v_mul_f32_e32 v236, v231, v231
	v_fma_f32 v236, v230, v230, v236
	v_mul_f32_e32 v237, v233, v233
	v_fma_f32 v237, v232, v232, v237
	v_add_f32_e32 v236, v236, v237
	v_add_f32_e32 v170, v170, v236
	s_waitcnt vmcnt(11)
	v_add_f32_e32 v226, v180, v184
	v_add_f32_e32 v227, v181, v185
	v_add_f32_e32 v228, v182, v186
	v_add_f32_e32 v229, v183, v187
	s_waitcnt vmcnt(10)
	v_add_f32_e32 v226, v226, v188
	v_add_f32_e32 v227, v227, v189
	v_add_f32_e32 v228, v228, v190
	v_add_f32_e32 v229, v229, v191
	s_waitcnt vmcnt(9)
; __device__ __forceinline__ float bf2f(u16 h) { return __uint_as_float(((unsigned)h) << 16); }
; __device__ __forceinline__ void phase_fixup(PP p, const int g_wid, const float alpha_in) {
;     ...
;       for (int ai = 0; ai < 2; ++ai)
; #pragma unroll
;         for (int m = 0; m < 4; ++m) {
;           const int q = ((ai * 2 + bj) * 4 + m) * 2 + n;
;           f32x4 s = pb[((long)pn * 32 + q) * 512];
; #pragma unroll
;           for (int ks = 1; ks < 11; ++ks) s += pb[((long)(ks * 4 + pn) * 32 + q) * 512];
;           const u16x4 ho = *reinterpret_cast<const u16x4*>(hbr + ai * 128 + m * 16);
;           float4 hv;
;           hv.x = bf2f(ho[0]) + alpha * s[0]; hv.y = bf2f(ho[1]) + alpha * s[1];
;           hv.z = bf2f(ho[2]) + alpha * s[2]; hv.w = bf2f(ho[3]) + alpha * s[3];
;           *reinterpret_cast<u16x4*>(hbr + ai * 128 + m * 16) = pack4(hv.x, hv.y, hv.z, hv.w);
;           sq += (hv.x * hv.x + hv.y * hv.y) + (hv.z * hv.z + hv.w * hv.w);
;         }
	v_add_f32_e32 v226, v226, v192
	v_add_f32_e32 v227, v227, v193
	v_add_f32_e32 v228, v228, v194
	v_add_f32_e32 v229, v229, v195
	s_waitcnt vmcnt(8)
	v_add_f32_e32 v226, v226, v196
	v_add_f32_e32 v227, v227, v197
	v_add_f32_e32 v228, v228, v198
	v_add_f32_e32 v229, v229, v199
	s_waitcnt vmcnt(7)
	v_add_f32_e32 v226, v226, v200
	v_add_f32_e32 v227, v227, v201
	v_add_f32_e32 v228, v228, v202
	v_add_f32_e32 v229, v229, v203
	s_waitcnt vmcnt(6)
	v_add_f32_e32 v226, v226, v204
	v_add_f32_e32 v227, v227, v205
	v_add_f32_e32 v228, v228, v206
	v_add_f32_e32 v229, v229, v207
	s_waitcnt vmcnt(5)
	v_add_f32_e32 v226, v226, v208
	v_add_f32_e32 v227, v227, v209
	v_add_f32_e32 v228, v228, v210
	v_add_f32_e32 v229, v229, v211
	s_waitcnt vmcnt(4)
	v_add_f32_e32 v226, v226, v212
	v_add_f32_e32 v227, v227, v213
	v_add_f32_e32 v228, v228, v214
	v_add_f32_e32 v229, v229, v215
	s_waitcnt vmcnt(3)
	v_add_f32_e32 v226, v226, v216
	v_add_f32_e32 v227, v227, v217
	v_add_f32_e32 v228, v228, v218
	v_add_f32_e32 v229, v229, v219
	s_waitcnt vmcnt(2)
	v_add_f32_e32 v226, v226, v220
	v_add_f32_e32 v227, v227, v221
	v_add_f32_e32 v228, v228, v222
	v_add_f32_e32 v229, v229, v223
	s_mov_b64 s[8:9], 0x24000
	v_lshl_add_u64 v[172:173], v[166:167], 0, s[8:9]
	global_load_dwordx4 v[180:183], v[172:173], off
	v_lshl_add_u64 v[172:173], v[172:173], 0, s[18:19]
	global_load_dwordx4 v[184:187], v[172:173], off
	v_lshl_add_u64 v[172:173], v[172:173], 0, s[18:19]
	global_load_dwordx4 v[188:191], v[172:173], off
	v_lshl_add_u64 v[172:173], v[172:173], 0, s[18:19]
	global_load_dwordx4 v[192:195], v[172:173], off
	v_lshl_add_u64 v[172:173], v[172:173], 0, s[18:19]
	global_load_dwordx4 v[196:199], v[172:173], off
	v_lshl_add_u64 v[172:173], v[172:173], 0, s[18:19]
	global_load_dwordx4 v[200:203], v[172:173], off
	v_lshl_add_u64 v[172:173], v[172:173], 0, s[18:19]
	global_load_dwordx4 v[204:207], v[172:173], off
	v_lshl_add_u64 v[172:173], v[172:173], 0, s[18:19]
	global_load_dwordx4 v[208:211], v[172:173], off
	v_lshl_add_u64 v[172:173], v[172:173], 0, s[18:19]
	global_load_dwordx4 v[212:215], v[172:173], off
	v_lshl_add_u64 v[172:173], v[172:173], 0, s[18:19]
	global_load_dwordx4 v[216:219], v[172:173], off
	v_lshl_add_u64 v[172:173], v[172:173], 0, s[18:19]
	global_load_dwordx4 v[220:223], v[172:173], off
	global_load_dwordx2 v[238:239], v[168:169], off offset:288
	s_waitcnt vmcnt(13)
	v_lshlrev_b32_e32 v230, 16, v224
	v_and_b32_e32 v231, 0xffff0000, v224
	v_lshlrev_b32_e32 v232, 16, v225
	v_and_b32_e32 v233, 0xffff0000, v225
	v_fma_f32 v230, 0.5, v226, v230
	v_fma_f32 v231, 0.5, v227, v231
	v_fma_f32 v232, 0.5, v228, v232
	v_fma_f32 v233, 0.5, v229, v233
	v_cvt_pk_bf16_f32 v234, v230, v231
	v_cvt_pk_bf16_f32 v235, v232, v233
	global_store_dwordx2 v[168:169], v[234:235], off offset:256
	v_mul_f32_e32 v236, v231, v231
	v_fma_f32 v236, v230, v230, v236
	v_mul_f32_e32 v237, v233, v233
	v_fma_f32 v237, v232, v232, v237
	v_add_f32_e32 v236, v236, v237
	v_add_f32_e32 v170, v170, v236
	s_waitcnt vmcnt(11)
	v_add_f32_e32 v226, v180, v184
	v_add_f32_e32 v227, v181, v185
	v_add_f32_e32 v228, v182, v186
	v_add_f32_e32 v229, v183, v187
	s_waitcnt vmcnt(10)
	v_add_f32_e32 v226, v226, v188
	v_add_f32_e32 v227, v227, v189
	v_add_f32_e32 v228, v228, v190
	v_add_f32_e32 v229, v229, v191
	s_waitcnt vmcnt(9)
	v_add_f32_e32 v226, v226, v192
	v_add_f32_e32 v227, v227, v193
	v_add_f32_e32 v228, v228, v194
	v_add_f32_e32 v229, v229, v195
	s_waitcnt vmcnt(8)
	v_add_f32_e32 v226, v226, v196
	v_add_f32_e32 v227, v227, v197
	v_add_f32_e32 v228, v228, v198
	v_add_f32_e32 v229, v229, v199
	s_waitcnt vmcnt(7)
	v_add_f32_e32 v226, v226, v200
	v_add_f32_e32 v227, v227, v201
	v_add_f32_e32 v228, v228, v202
	v_add_f32_e32 v229, v229, v203
	s_waitcnt vmcnt(6)
	v_add_f32_e32 v226, v226, v204
	v_add_f32_e32 v227, v227, v205
	v_add_f32_e32 v228, v228, v206
	v_add_f32_e32 v229, v229, v207
	s_waitcnt vmcnt(5)
	v_add_f32_e32 v226, v226, v208
	v_add_f32_e32 v227, v227, v209
	v_add_f32_e32 v228, v228, v210
	v_add_f32_e32 v229, v229, v211
	s_waitcnt vmcnt(4)
	v_add_f32_e32 v226, v226, v212
	v_add_f32_e32 v227, v227, v213
	v_add_f32_e32 v228, v228, v214
	v_add_f32_e32 v229, v229, v215
	s_waitcnt vmcnt(3)
	v_add_f32_e32 v226, v226, v216
	v_add_f32_e32 v227, v227, v217
	v_add_f32_e32 v228, v228, v218
	v_add_f32_e32 v229, v229, v219
	s_waitcnt vmcnt(2)
	v_add_f32_e32 v226, v226, v220
	v_add_f32_e32 v227, v227, v221
	v_add_f32_e32 v228, v228, v222
	v_add_f32_e32 v229, v229, v223
	s_mov_b64 s[8:9], 0x28000
	v_lshl_add_u64 v[172:173], v[166:167], 0, s[8:9]
	global_load_dwordx4 v[180:183], v[172:173], off
	v_lshl_add_u64 v[172:173], v[172:173], 0, s[18:19]
	global_load_dwordx4 v[184:187], v[172:173], off
	v_lshl_add_u64 v[172:173], v[172:173], 0, s[18:19]
	global_load_dwordx4 v[188:191], v[172:173], off
	v_lshl_add_u64 v[172:173], v[172:173], 0, s[18:19]
	global_load_dwordx4 v[192:195], v[172:173], off
	v_lshl_add_u64 v[172:173], v[172:173], 0, s[18:19]
	global_load_dwordx4 v[196:199], v[172:173], off
	v_lshl_add_u64 v[172:173], v[172:173], 0, s[18:19]
	global_load_dwordx4 v[200:203], v[172:173], off
	v_lshl_add_u64 v[172:173], v[172:173], 0, s[18:19]
	global_load_dwordx4 v[204:207], v[172:173], off
	v_lshl_add_u64 v[172:173], v[172:173], 0, s[18:19]
	global_load_dwordx4 v[208:211], v[172:173], off
	v_lshl_add_u64 v[172:173], v[172:173], 0, s[18:19]
	global_load_dwordx4 v[212:215], v[172:173], off
	v_lshl_add_u64 v[172:173], v[172:173], 0, s[18:19]
	global_load_dwordx4 v[216:219], v[172:173], off
	v_lshl_add_u64 v[172:173], v[172:173], 0, s[18:19]
	global_load_dwordx4 v[220:223], v[172:173], off
	global_load_dwordx2 v[224:225], v[168:169], off offset:320
	s_waitcnt vmcnt(13)
; __device__ __forceinline__ float bf2f(u16 h) { return __uint_as_float(((unsigned)h) << 16); }
; __device__ __forceinline__ void phase_fixup(PP p, const int g_wid, const float alpha_in) {
;     ...
;           for (int ks = 1; ks < 11; ++ks) s += pb[((long)(ks * 4 + pn) * 32 + q) * 512];
;           const u16x4 ho = *reinterpret_cast<const u16x4*>(hbr + ai * 128 + m * 16);
;           float4 hv;
;           hv.x = bf2f(ho[0]) + alpha * s[0]; hv.y = bf2f(ho[1]) + alpha * s[1];
;           hv.z = bf2f(ho[2]) + alpha * s[2]; hv.w = bf2f(ho[3]) + alpha * s[3];
;           *reinterpret_cast<u16x4*>(hbr + ai * 128 + m * 16) = pack4(hv.x, hv.y, hv.z, hv.w);
;           sq += (hv.x * hv.x + hv.y * hv.y) + (hv.z * hv.z + hv.w * hv.w);
;         }
	v_lshlrev_b32_e32 v230, 16, v238
	v_and_b32_e32 v231, 0xffff0000, v238
	v_lshlrev_b32_e32 v232, 16, v239
	v_and_b32_e32 v233, 0xffff0000, v239
	v_fma_f32 v230, 0.5, v226, v230
	v_fma_f32 v231, 0.5, v227, v231
	v_fma_f32 v232, 0.5, v228, v232
	v_fma_f32 v233, 0.5, v229, v233
	v_cvt_pk_bf16_f32 v234, v230, v231
	v_cvt_pk_bf16_f32 v235, v232, v233
	global_store_dwordx2 v[168:169], v[234:235], off offset:288
	v_mul_f32_e32 v236, v231, v231
	v_fma_f32 v236, v230, v230, v236
	v_mul_f32_e32 v237, v233, v233
	v_fma_f32 v237, v232, v232, v237
	v_add_f32_e32 v236, v236, v237
	v_add_f32_e32 v170, v170, v236
	s_waitcnt vmcnt(11)
	v_add_f32_e32 v226, v180, v184
	v_add_f32_e32 v227, v181, v185
	v_add_f32_e32 v228, v182, v186
	v_add_f32_e32 v229, v183, v187
	s_waitcnt vmcnt(10)
	v_add_f32_e32 v226, v226, v188
	v_add_f32_e32 v227, v227, v189
	v_add_f32_e32 v228, v228, v190
	v_add_f32_e32 v229, v229, v191
	s_waitcnt vmcnt(9)
	v_add_f32_e32 v226, v226, v192
	v_add_f32_e32 v227, v227, v193
	v_add_f32_e32 v228, v228, v194
	v_add_f32_e32 v229, v229, v195
	s_waitcnt vmcnt(8)
	v_add_f32_e32 v226, v226, v196
	v_add_f32_e32 v227, v227, v197
	v_add_f32_e32 v228, v228, v198
	v_add_f32_e32 v229, v229, v199
	s_waitcnt vmcnt(7)
	v_add_f32_e32 v226, v226, v200
	v_add_f32_e32 v227, v227, v201
	v_add_f32_e32 v228, v228, v202
	v_add_f32_e32 v229, v229, v203
	s_waitcnt vmcnt(6)
	v_add_f32_e32 v226, v226, v204
	v_add_f32_e32 v227, v227, v205
	v_add_f32_e32 v228, v228, v206
	v_add_f32_e32 v229, v229, v207
	s_waitcnt vmcnt(5)
	v_add_f32_e32 v226, v226, v208
	v_add_f32_e32 v227, v227, v209
	v_add_f32_e32 v228, v228, v210
	v_add_f32_e32 v229, v229, v211
	s_waitcnt vmcnt(4)
	v_add_f32_e32 v226, v226, v212
	v_add_f32_e32 v227, v227, v213
	v_add_f32_e32 v228, v228, v214
	v_add_f32_e32 v229, v229, v215
	s_waitcnt vmcnt(3)
	v_add_f32_e32 v226, v226, v216
	v_add_f32_e32 v227, v227, v217
	v_add_f32_e32 v228, v228, v218
	v_add_f32_e32 v229, v229, v219
	s_waitcnt vmcnt(2)
	v_add_f32_e32 v226, v226, v220
	v_add_f32_e32 v227, v227, v221
	v_add_f32_e32 v228, v228, v222
	v_add_f32_e32 v229, v229, v223
	s_mov_b64 s[8:9], 0x2c000
	v_lshl_add_u64 v[172:173], v[166:167], 0, s[8:9]
	global_load_dwordx4 v[180:183], v[172:173], off
	v_lshl_add_u64 v[172:173], v[172:173], 0, s[18:19]
	global_load_dwordx4 v[184:187], v[172:173], off
	v_lshl_add_u64 v[172:173], v[172:173], 0, s[18:19]
	global_load_dwordx4 v[188:191], v[172:173], off
	v_lshl_add_u64 v[172:173], v[172:173], 0, s[18:19]
	global_load_dwordx4 v[192:195], v[172:173], off
	v_lshl_add_u64 v[172:173], v[172:173], 0, s[18:19]
	global_load_dwordx4 v[196:199], v[172:173], off
	v_lshl_add_u64 v[172:173], v[172:173], 0, s[18:19]
	global_load_dwordx4 v[200:203], v[172:173], off
	v_lshl_add_u64 v[172:173], v[172:173], 0, s[18:19]
	global_load_dwordx4 v[204:207], v[172:173], off
	v_lshl_add_u64 v[172:173], v[172:173], 0, s[18:19]
	global_load_dwordx4 v[208:211], v[172:173], off
	v_lshl_add_u64 v[172:173], v[172:173], 0, s[18:19]
	global_load_dwordx4 v[212:215], v[172:173], off
	v_lshl_add_u64 v[172:173], v[172:173], 0, s[18:19]
	global_load_dwordx4 v[216:219], v[172:173], off
	v_lshl_add_u64 v[172:173], v[172:173], 0, s[18:19]
	global_load_dwordx4 v[220:223], v[172:173], off
	global_load_dwordx2 v[238:239], v[168:169], off offset:352
	s_waitcnt vmcnt(13)
	v_lshlrev_b32_e32 v230, 16, v224
	v_and_b32_e32 v231, 0xffff0000, v224
	v_lshlrev_b32_e32 v232, 16, v225
	v_and_b32_e32 v233, 0xffff0000, v225
	v_fma_f32 v230, 0.5, v226, v230
	v_fma_f32 v231, 0.5, v227, v231
	v_fma_f32 v232, 0.5, v228, v232
	v_fma_f32 v233, 0.5, v229, v233
	v_cvt_pk_bf16_f32 v234, v230, v231
	v_cvt_pk_bf16_f32 v235, v232, v233
	global_store_dwordx2 v[168:169], v[234:235], off offset:320
	v_mul_f32_e32 v236, v231, v231
	v_fma_f32 v236, v230, v230, v236
	v_mul_f32_e32 v237, v233, v233
	v_fma_f32 v237, v232, v232, v237
	v_add_f32_e32 v236, v236, v237
	v_add_f32_e32 v170, v170, v236
	s_waitcnt vmcnt(11)
	v_add_f32_e32 v226, v180, v184
	v_add_f32_e32 v227, v181, v185
	v_add_f32_e32 v228, v182, v186
	v_add_f32_e32 v229, v183, v187
	s_waitcnt vmcnt(10)
	v_add_f32_e32 v226, v226, v188
	v_add_f32_e32 v227, v227, v189
	v_add_f32_e32 v228, v228, v190
	v_add_f32_e32 v229, v229, v191
	s_waitcnt vmcnt(9)
	v_add_f32_e32 v226, v226, v192
	v_add_f32_e32 v227, v227, v193
	v_add_f32_e32 v228, v228, v194
	v_add_f32_e32 v229, v229, v195
	s_waitcnt vmcnt(8)
	v_add_f32_e32 v226, v226, v196
	v_add_f32_e32 v227, v227, v197
	v_add_f32_e32 v228, v228, v198
	v_add_f32_e32 v229, v229, v199
	s_waitcnt vmcnt(7)
	v_add_f32_e32 v226, v226, v200
	v_add_f32_e32 v227, v227, v201
	v_add_f32_e32 v228, v228, v202
	v_add_f32_e32 v229, v229, v203
	s_waitcnt vmcnt(6)
	v_add_f32_e32 v226, v226, v204
	v_add_f32_e32 v227, v227, v205
	v_add_f32_e32 v228, v228, v206
	v_add_f32_e32 v229, v229, v207
	s_waitcnt vmcnt(5)
	v_add_f32_e32 v226, v226, v208
	v_add_f32_e32 v227, v227, v209
	v_add_f32_e32 v228, v228, v210
	v_add_f32_e32 v229, v229, v211
	s_waitcnt vmcnt(4)
	v_add_f32_e32 v226, v226, v212
	v_add_f32_e32 v227, v227, v213
	v_add_f32_e32 v228, v228, v214
	v_add_f32_e32 v229, v229, v215
	s_waitcnt vmcnt(3)
	v_add_f32_e32 v226, v226, v216
	v_add_f32_e32 v227, v227, v217
	v_add_f32_e32 v228, v228, v218
	v_add_f32_e32 v229, v229, v219
	s_waitcnt vmcnt(2)
	v_add_f32_e32 v226, v226, v220
	v_add_f32_e32 v227, v227, v221
	v_add_f32_e32 v228, v228, v222
	v_add_f32_e32 v229, v229, v223
	s_waitcnt vmcnt(1)
	v_lshlrev_b32_e32 v230, 16, v238
	v_and_b32_e32 v231, 0xffff0000, v238
	v_lshlrev_b32_e32 v232, 16, v239
	v_and_b32_e32 v233, 0xffff0000, v239
	v_fma_f32 v230, 0.5, v226, v230
	v_fma_f32 v231, 0.5, v227, v231
	v_fma_f32 v232, 0.5, v228, v232
	v_fma_f32 v233, 0.5, v229, v233
	v_cvt_pk_bf16_f32 v234, v230, v231
	v_cvt_pk_bf16_f32 v235, v232, v233
	global_store_dwordx2 v[168:169], v[234:235], off offset:352
	v_mul_f32_e32 v236, v231, v231
	v_fma_f32 v236, v230, v230, v236
	v_mul_f32_e32 v237, v233, v233
	v_fma_f32 v237, v232, v232, v237
	v_add_f32_e32 v236, v236, v237
	v_add_f32_e32 v170, v170, v236

; __device__ __forceinline__ unsigned xb_add(unsigned* p, unsigned v) { return __hip_atomic_fetch_add(p, v, __ATOMIC_RELAXED, __HIP_MEMORY_SCOPE_AGENT); }
; __device__ __forceinline__ void phase_fixup(PP p, const int g_wid, const float alpha_in) {
;     ...
;     sq += __shfl_xor(sq, 16); sq += __shfl_xor(sq, 32);
;     if (ok && fq == 0) ssq[(long)row * 16 + pn * 4 + wr] = sq;
; __device__ __forceinline__ void xcd_barrier(const XcdBarrier& b, int tid, const unsigned gen) {
;   asm volatile("s_waitcnt vmcnt(0)" ::: "memory");
;   __syncthreads();
;   if (tid == 0) {
;     unsigned* bar = b.bar;
;     __builtin_amdgcn_s_waitcnt(0);
;     const unsigned old = xb_add(&bar[XB_XSUB(b.x)], 1u);
.Lfx2_done:
	s_or_b64 exec, exec, s[16:17]
.LBB0_617:
	s_nop 0
	v_mbcnt_lo_u32_b32 v0, s10, 0
	v_mbcnt_hi_u32_b32 v0, s10, v0
	v_or_b32_e32 v0, s33, v0
	s_waitcnt vmcnt(0)
	s_waitcnt lgkmcnt(0)
	v_cmp_eq_u32_e32 vcc, 0, v0
	s_barrier
	s_and_saveexec_b64 s[0:1], vcc
	s_cbranch_execz .LBB0_654
	s_mov_b64 s[2:3], exec
	v_mbcnt_lo_u32_b32 v0, s2, 0
	v_mbcnt_hi_u32_b32 v0, s3, v0
	s_lshl_b32 s20, s26, 6
	s_mov_b32 s7, 0
	v_cmp_eq_u32_e32 vcc, 0, v0
	s_waitcnt vmcnt(0) expcnt(0) lgkmcnt(0)
	s_and_saveexec_b64 s[4:5], vcc
	s_cbranch_execz .LBB0_620
	s_add_i32 s6, s20, 0x500
	s_lshl_b64 s[6:7], s[6:7], 2
	s_add_u32 s6, s24, s6
	s_addc_u32 s7, s25, s7
	s_bcnt1_i32_b64 s2, s[2:3]
	v_mov_b32_e32 v1, 0
	v_mov_b32_e32 v2, s2
	global_atomic_add v1, v1, v2, s[6:7] sc0
